# norm phase fully hand-written: gate pre-activation GEMV register-blocked with wave reduce-scatter (was 78us, serial per-row loads and 96 bpermutes), condition-straddling rows handled in the fast path
# speedup vs baseline: 1.0283x; 1.0129x over previous
.LBB0_899:
	s_andn2_b64 vcc, exec, s[68:69]
	s_cbranch_vccnz .LBB0_1130
	v_readlane_b32 s0, v255, 11
	s_cmp_gt_i32 s0, 0
	s_mov_b64 s[2:3], -1
	s_cbranch_scc0 .LBB0_1013
	s_mov_b32 s0, s67
	s_mov_b32 s79, s0
	s_lshl_b32 s1, s0, 3
	v_readlane_b32 s0, v254, 63
	v_writelane_b32 v255, s58, 22
	s_add_i32 s1, s1, s0
	s_mov_b32 s67, 0x7f800000
	v_writelane_b32 v255, s59, 23
	v_mov_b32_e32 v0, v1
	s_cmpk_gt_i32 s1, 0x7ff
	s_cbranch_scc1 .LBB0_1012
	s_mov_b32 s100, s80
	s_ashr_i32 s0, s80, 2
	s_and_b32 s8, s80, 3
	s_cmp_eq_u32 s80, 1
	v_readlane_b32 s10, v255, 14
	s_cselect_b64 s[56:57], -1, 0
	s_or_b32 s2, s8, s0
	v_readlane_b32 s11, v255, 15
	s_cmp_lg_u32 s2, 0
	s_load_dwordx2 s[2:3], s[10:11], 0x58
	s_mul_i32 s0, s0, 3
	s_cselect_b64 s[94:95], -1, 0
	s_add_i32 s6, s0, s8
	s_ashr_i32 s7, s6, 31
	s_lshl_b64 s[6:7], s[6:7], 12
	s_waitcnt lgkmcnt(0)
	s_add_u32 s2, s2, s6
	s_addc_u32 s3, s3, s7
	v_mbcnt_lo_u32_b32 v0, -1, v0
	s_add_u32 s70, s10, 8
	v_mbcnt_hi_u32_b32 v92, -1, v0
	s_addc_u32 s71, s11, 0
	s_mulk_i32 s8, 0x3000
	v_readlane_b32 s6, v255, 22
	s_mul_i32 s80, s1, 6
	v_lshlrev_b32_e32 v94, 3, v92
	s_add_u32 s1, s6, s8
	v_ashrrev_i32_e32 v93, 31, v92
	v_readlane_b32 s8, v255, 5
	v_ashrrev_i32_e32 v95, 31, v94
	s_waitcnt vmcnt(0)
	v_lshlrev_b64 v[4:5], 2, v[92:93]
	v_readlane_b32 s10, v255, 7
	v_readlane_b32 s11, v255, 8
	v_lshl_add_u64 v[100:101], v[94:95], 2, s[2:3]
	v_lshlrev_b64 v[102:103], 5, v[94:95]
	v_lshl_add_u64 v[6:7], s[10:11], 0, v[4:5]
	s_mov_b64 s[10:11], 0x200000
	s_mov_b64 s[2:3], 0x4000
	v_readlane_b32 s7, v255, 23
	v_lshl_add_u64 v[98:99], v[6:7], 0, s[10:11]
	v_or_b32_e32 v6, 4, v94
	v_lshl_add_u64 v[104:105], v[102:103], 0, s[2:3]
	s_mov_b64 s[2:3], 0x4040
	s_addc_u32 s54, s7, 0
	v_ashrrev_i32_e32 v7, 31, v6
	v_lshl_add_u64 v[114:115], v[102:103], 0, s[2:3]
	s_mov_b64 s[2:3], 0x40c0
	s_ashr_i32 s81, s80, 31
	v_readlane_b32 s6, v255, 9
	v_lshlrev_b32_e32 v0, 2, v92
	v_add_u32_e32 v106, 0x204, v94
	v_or_b32_e32 v8, 2, v94
	v_lshlrev_b64 v[110:111], 5, v[6:7]
	v_or_b32_e32 v6, 6, v94
	v_lshl_add_u64 v[118:119], v[102:103], 0, s[2:3]
	s_lshl_b64 s[2:3], s[80:81], 6
	v_lshlrev_b64 v[2:3], 1, v[94:95]
	v_readlane_b32 s7, v255, 10
	v_xor_b32_e32 v126, 4, v0
	v_xor_b32_e32 v127, 8, v0
	v_xor_b32_e32 v128, 16, v0
	v_xor_b32_e32 v129, 32, v0
	v_xor_b32_e32 v130, 64, v0
	v_xor_b32_e32 v131, 0x80, v0
	v_and_b32_e32 v0, 4, v92
	v_ashrrev_i32_e32 v107, 31, v106
	v_ashrrev_i32_e32 v9, 31, v8
	v_ashrrev_i32_e32 v7, 31, v6
	v_lshl_add_u64 v[120:121], s[2:3], 0, v[4:5]
	s_lshl_b64 s[2:3], s[80:81], 11
	v_lshl_add_u64 v[96:97], s[6:7], 0, v[2:3]
	v_cmp_gt_i32_e64 s[6:7], 16, v92
	v_cmp_ne_u32_e64 s[74:75], 0, v0
	v_lshlrev_b64 v[108:109], 5, v[8:9]
	v_lshlrev_b64 v[112:113], 5, v[6:7]
	v_lshlrev_b64 v[116:117], 5, v[106:107]
	v_cmp_eq_u32_e64 s[68:69], 15, v92
	v_cmp_eq_u32_e64 s[12:13], 14, v92
	v_cmp_eq_u32_e64 s[14:15], 13, v92
	v_cmp_eq_u32_e64 s[16:17], 12, v92
	v_cmp_eq_u32_e64 s[18:19], 11, v92
	v_cmp_eq_u32_e64 s[20:21], 10, v92
	v_cmp_eq_u32_e64 s[22:23], 9, v92
	v_cmp_eq_u32_e64 s[24:25], 8, v92
	v_cmp_eq_u32_e64 s[26:27], 7, v92
	v_cmp_eq_u32_e64 s[28:29], 6, v92
	v_cmp_eq_u32_e64 s[30:31], 5, v92
	v_cmp_eq_u32_e64 s[34:35], 4, v92
	v_cmp_eq_u32_e64 s[36:37], 3, v92
	v_cmp_eq_u32_e64 s[38:39], 2, v92
	v_cmp_eq_u32_e64 s[40:41], 1, v92
	v_cmp_eq_u32_e64 s[42:43], 0, v92
	v_lshl_add_u64 v[122:123], s[2:3], 0, v[2:3]
	v_readlane_b32 s9, v255, 6
	s_sub_i32 s1, s80, 0x1800
	s_max_i32 s1, s1, 0
	s_lshr_b32 s1, s1, 11
	s_sub_i32 s3, s80, 0x17fb
	s_max_i32 s3, s3, 0
	s_lshr_b32 s3, s3, 11
	s_mov_b32 s2, 6
	s_cmp_eq_u32 s1, s3
	s_cbranch_scc1 .Lnrm_n0
	s_lshl_b32 s2, s3, 11
	s_add_i32 s2, s2, 0x1800
	s_sub_i32 s2, s2, s80
.Lnrm_n0:
	s_ashr_i32 s0, s100, 2
	s_and_b32 s6, s100, 3
	s_mul_i32 s7, s0, 3
	s_add_i32 s8, s7, s6
	v_readlane_b32 s10, v255, 14
	v_readlane_b32 s11, v255, 15
	s_load_dwordx2 s[12:13], s[10:11], 0x58
	s_load_dwordx4 s[16:19], s[10:11], 0x0
	s_load_dwordx4 s[44:47], s[10:11], 0x88
	s_add_i32 s9, s7, s1
	s_mul_i32 s9, s9, 0x9000
	s_mul_i32 s14, s6, 0x3000
	s_add_i32 s9, s9, s14
	s_add_i32 s9, s9, 0x100000
	v_readlane_b32 s20, v255, 7
	v_readlane_b32 s21, v255, 8
	s_add_u32 s20, s20, s9
	s_addc_u32 s21, s21, 0
	v_lshlrev_b32_e32 v82, 5, v92
	v_lshlrev_b32_e32 v83, 4, v92
	s_lshl_b64 s[22:23], s[80:81], 12
	v_readlane_b32 s24, v255, 5
	v_readlane_b32 s25, v255, 6
	s_waitcnt lgkmcnt(0)
	s_and_b64 vcc, exec, s[94:95]
	s_cbranch_vccnz .Lnrm_src
	s_mov_b64 s[24:25], s[16:17]
	s_cmp_eq_u32 s1, 0
	s_cbranch_scc1 .Lnrm_src
	s_add_u32 s24, s18, 0xfe000000
	s_addc_u32 s25, s19, -1
.Lnrm_src:
	s_add_u32 s24, s24, s22
	s_addc_u32 s25, s25, s23
	global_load_dwordx4 v[2:5], v82, s[24:25] offset:0
	global_load_dwordx4 v[6:9], v82, s[24:25] offset:16
	global_load_dwordx4 v[10:13], v82, s[24:25] offset:2048
	global_load_dwordx4 v[14:17], v82, s[24:25] offset:2064
	s_add_u32 s24, s24, 0x1000
	s_addc_u32 s25, s25, 0
	s_cmp_lg_u32 s2, 1
	s_cbranch_scc1 .Lnrm_ld1
	s_and_b64 vcc, exec, s[94:95]
	s_cbranch_vccnz .Lnrm_ld1
	s_add_u32 s24, s18, 0xfe000000
	s_addc_u32 s25, s19, -1
	s_add_u32 s28, s22, 0x1000
	s_addc_u32 s54, s23, 0
	s_add_u32 s24, s24, s28
	s_addc_u32 s25, s25, s54
.Lnrm_ld1:
	global_load_dwordx4 v[18:21], v82, s[24:25] offset:0
	global_load_dwordx4 v[22:25], v82, s[24:25] offset:16
	global_load_dwordx4 v[26:29], v82, s[24:25] offset:2048
	global_load_dwordx4 v[30:33], v82, s[24:25] offset:2064
	s_add_u32 s24, s24, 0x1000
	s_addc_u32 s25, s25, 0
	s_cmp_lg_u32 s2, 2
	s_cbranch_scc1 .Lnrm_ld2
	s_and_b64 vcc, exec, s[94:95]
	s_cbranch_vccnz .Lnrm_ld2
	s_add_u32 s24, s18, 0xfe000000
	s_addc_u32 s25, s19, -1
	s_add_u32 s28, s22, 0x2000
	s_addc_u32 s54, s23, 0
	s_add_u32 s24, s24, s28
	s_addc_u32 s25, s25, s54
.Lnrm_ld2:
	global_load_dwordx4 v[34:37], v82, s[24:25] offset:0
	global_load_dwordx4 v[38:41], v82, s[24:25] offset:16
	global_load_dwordx4 v[42:45], v82, s[24:25] offset:2048
	global_load_dwordx4 v[46:49], v82, s[24:25] offset:2064
	s_add_u32 s24, s24, 0x1000
	s_addc_u32 s25, s25, 0
	s_cmp_lg_u32 s2, 3
	s_cbranch_scc1 .Lnrm_ld3
	s_and_b64 vcc, exec, s[94:95]
	s_cbranch_vccnz .Lnrm_ld3
	s_add_u32 s24, s18, 0xfe000000
	s_addc_u32 s25, s19, -1
	s_add_u32 s28, s22, 0x3000
	s_addc_u32 s54, s23, 0
	s_add_u32 s24, s24, s28
	s_addc_u32 s25, s25, s54
.Lnrm_ld3:
	global_load_dwordx4 v[50:53], v82, s[24:25] offset:0
	global_load_dwordx4 v[54:57], v82, s[24:25] offset:16
	global_load_dwordx4 v[58:61], v82, s[24:25] offset:2048
	global_load_dwordx4 v[62:65], v82, s[24:25] offset:2064
	s_add_u32 s24, s24, 0x1000
	s_addc_u32 s25, s25, 0
	s_cmp_lg_u32 s2, 4
	s_cbranch_scc1 .Lnrm_ld4
	s_and_b64 vcc, exec, s[94:95]
	s_cbranch_vccnz .Lnrm_ld4
	s_add_u32 s24, s18, 0xfe000000
	s_addc_u32 s25, s19, -1
	s_add_u32 s28, s22, 0x4000
	s_addc_u32 s54, s23, 0
	s_add_u32 s24, s24, s28
	s_addc_u32 s25, s25, s54
.Lnrm_ld4:
	global_load_dwordx4 v[66:69], v82, s[24:25] offset:0
	global_load_dwordx4 v[70:73], v82, s[24:25] offset:16
	global_load_dwordx4 v[74:77], v82, s[24:25] offset:2048
	global_load_dwordx4 v[78:81], v82, s[24:25] offset:2064
	s_add_u32 s24, s24, 0x1000
	s_addc_u32 s25, s25, 0
	s_cmp_lg_u32 s2, 5
	s_cbranch_scc1 .Lnrm_ld5
	s_and_b64 vcc, exec, s[94:95]
	s_cbranch_vccnz .Lnrm_ld5
	s_add_u32 s24, s18, 0xfe000000
	s_addc_u32 s25, s19, -1
	s_add_u32 s28, s22, 0x5000
	s_addc_u32 s54, s23, 0
	s_add_u32 s24, s24, s28
	s_addc_u32 s25, s25, s54
.Lnrm_ld5:
	global_load_dwordx4 v[132:135], v82, s[24:25] offset:0
	global_load_dwordx4 v[136:139], v82, s[24:25] offset:16
	global_load_dwordx4 v[140:143], v82, s[24:25] offset:2048
	global_load_dwordx4 v[144:147], v82, s[24:25] offset:2064
	s_lshl_b32 s8, s8, 12
	s_add_u32 s12, s12, s8
	s_addc_u32 s13, s13, 0
	s_add_u32 s26, s20, 0x1000
	s_addc_u32 s27, s21, 0
	global_load_dwordx4 v[148:151], v82, s[12:13] offset:0
	global_load_dwordx4 v[170:173], v82, s[26:27] offset:0
	global_load_dwordx4 v[186:189], v82, s[20:21] offset:0
	global_load_dwordx4 v[152:155], v82, s[12:13] offset:16
	global_load_dwordx4 v[174:177], v82, s[26:27] offset:16
	global_load_dwordx4 v[190:193], v82, s[20:21] offset:16
	global_load_dwordx4 v[156:159], v82, s[12:13] offset:2048
	global_load_dwordx4 v[178:181], v82, s[26:27] offset:2048
	global_load_dwordx4 v[194:197], v82, s[20:21] offset:2048
	global_load_dwordx4 v[160:163], v82, s[12:13] offset:2064
	global_load_dwordx4 v[182:185], v82, s[26:27] offset:2064
	global_load_dwordx4 v[198:201], v82, s[20:21] offset:2064
	s_mov_b32 s28, 0x3a800000
	s_waitcnt vmcnt(32)
	v_mul_f32_e32 v202, v2, v2
	v_fmac_f32_e32 v202, v3, v3
	v_fmac_f32_e32 v202, v4, v4
	v_fmac_f32_e32 v202, v5, v5
	v_fmac_f32_e32 v202, v6, v6
	v_fmac_f32_e32 v202, v7, v7
	v_fmac_f32_e32 v202, v8, v8
	v_fmac_f32_e32 v202, v9, v9
	v_fmac_f32_e32 v202, v10, v10
	v_fmac_f32_e32 v202, v11, v11
	v_fmac_f32_e32 v202, v12, v12
	v_fmac_f32_e32 v202, v13, v13
	v_fmac_f32_e32 v202, v14, v14
	v_fmac_f32_e32 v202, v15, v15
	v_fmac_f32_e32 v202, v16, v16
	v_fmac_f32_e32 v202, v17, v17
	s_waitcnt vmcnt(28)
	v_mul_f32_e32 v203, v18, v18
	v_fmac_f32_e32 v203, v19, v19
	v_fmac_f32_e32 v203, v20, v20
	v_fmac_f32_e32 v203, v21, v21
	v_fmac_f32_e32 v203, v22, v22
	v_fmac_f32_e32 v203, v23, v23
	v_fmac_f32_e32 v203, v24, v24
	v_fmac_f32_e32 v203, v25, v25
	v_fmac_f32_e32 v203, v26, v26
	v_fmac_f32_e32 v203, v27, v27
	v_fmac_f32_e32 v203, v28, v28
	v_fmac_f32_e32 v203, v29, v29
	v_fmac_f32_e32 v203, v30, v30
	v_fmac_f32_e32 v203, v31, v31
	v_fmac_f32_e32 v203, v32, v32
	v_fmac_f32_e32 v203, v33, v33
	s_waitcnt vmcnt(24)
	v_mul_f32_e32 v204, v34, v34
	v_fmac_f32_e32 v204, v35, v35
	v_fmac_f32_e32 v204, v36, v36
	v_fmac_f32_e32 v204, v37, v37
	v_fmac_f32_e32 v204, v38, v38
	v_fmac_f32_e32 v204, v39, v39
	v_fmac_f32_e32 v204, v40, v40
	v_fmac_f32_e32 v204, v41, v41
	v_fmac_f32_e32 v204, v42, v42
	v_fmac_f32_e32 v204, v43, v43
	v_fmac_f32_e32 v204, v44, v44
	v_fmac_f32_e32 v204, v45, v45
	v_fmac_f32_e32 v204, v46, v46
	v_fmac_f32_e32 v204, v47, v47
	v_fmac_f32_e32 v204, v48, v48
	v_fmac_f32_e32 v204, v49, v49
	s_waitcnt vmcnt(20)
	v_mul_f32_e32 v205, v50, v50
	v_fmac_f32_e32 v205, v51, v51
	v_fmac_f32_e32 v205, v52, v52
	v_fmac_f32_e32 v205, v53, v53
	v_fmac_f32_e32 v205, v54, v54
	v_fmac_f32_e32 v205, v55, v55
	v_fmac_f32_e32 v205, v56, v56
	v_fmac_f32_e32 v205, v57, v57
	v_fmac_f32_e32 v205, v58, v58
	v_fmac_f32_e32 v205, v59, v59
	v_fmac_f32_e32 v205, v60, v60
	v_fmac_f32_e32 v205, v61, v61
	v_fmac_f32_e32 v205, v62, v62
	v_fmac_f32_e32 v205, v63, v63
	v_fmac_f32_e32 v205, v64, v64
	v_fmac_f32_e32 v205, v65, v65
	s_waitcnt vmcnt(16)
	v_mul_f32_e32 v206, v66, v66
	v_fmac_f32_e32 v206, v67, v67
	v_fmac_f32_e32 v206, v68, v68
	v_fmac_f32_e32 v206, v69, v69
	v_fmac_f32_e32 v206, v70, v70
	v_fmac_f32_e32 v206, v71, v71
	v_fmac_f32_e32 v206, v72, v72
	v_fmac_f32_e32 v206, v73, v73
	v_fmac_f32_e32 v206, v74, v74
	v_fmac_f32_e32 v206, v75, v75
	v_fmac_f32_e32 v206, v76, v76
	v_fmac_f32_e32 v206, v77, v77
	v_fmac_f32_e32 v206, v78, v78
	v_fmac_f32_e32 v206, v79, v79
	v_fmac_f32_e32 v206, v80, v80
	v_fmac_f32_e32 v206, v81, v81
	s_waitcnt vmcnt(12)
	v_mul_f32_e32 v207, v132, v132
	v_fmac_f32_e32 v207, v133, v133
	v_fmac_f32_e32 v207, v134, v134
	v_fmac_f32_e32 v207, v135, v135
	v_fmac_f32_e32 v207, v136, v136
	v_fmac_f32_e32 v207, v137, v137
	v_fmac_f32_e32 v207, v138, v138
	v_fmac_f32_e32 v207, v139, v139
	v_fmac_f32_e32 v207, v140, v140
	v_fmac_f32_e32 v207, v141, v141
	v_fmac_f32_e32 v207, v142, v142
	v_fmac_f32_e32 v207, v143, v143
	v_fmac_f32_e32 v207, v144, v144
	v_fmac_f32_e32 v207, v145, v145
	v_fmac_f32_e32 v207, v146, v146
	v_fmac_f32_e32 v207, v147, v147
	s_nop 1
	v_add_f32_dpp v202, v202, v202 row_ror:8 row_mask:0xf bank_mask:0xf
	v_add_f32_dpp v203, v203, v203 row_ror:8 row_mask:0xf bank_mask:0xf
	v_add_f32_dpp v204, v204, v204 row_ror:8 row_mask:0xf bank_mask:0xf
	v_add_f32_dpp v205, v205, v205 row_ror:8 row_mask:0xf bank_mask:0xf
	v_add_f32_dpp v206, v206, v206 row_ror:8 row_mask:0xf bank_mask:0xf
	v_add_f32_dpp v207, v207, v207 row_ror:8 row_mask:0xf bank_mask:0xf
	v_add_f32_dpp v202, v202, v202 row_ror:4 row_mask:0xf bank_mask:0xf
	v_add_f32_dpp v203, v203, v203 row_ror:4 row_mask:0xf bank_mask:0xf
	v_add_f32_dpp v204, v204, v204 row_ror:4 row_mask:0xf bank_mask:0xf
	v_add_f32_dpp v205, v205, v205 row_ror:4 row_mask:0xf bank_mask:0xf
	v_add_f32_dpp v206, v206, v206 row_ror:4 row_mask:0xf bank_mask:0xf
	v_add_f32_dpp v207, v207, v207 row_ror:4 row_mask:0xf bank_mask:0xf
	v_add_f32_dpp v202, v202, v202 row_ror:2 row_mask:0xf bank_mask:0xf
	v_add_f32_dpp v203, v203, v203 row_ror:2 row_mask:0xf bank_mask:0xf
	v_add_f32_dpp v204, v204, v204 row_ror:2 row_mask:0xf bank_mask:0xf
	v_add_f32_dpp v205, v205, v205 row_ror:2 row_mask:0xf bank_mask:0xf
	v_add_f32_dpp v206, v206, v206 row_ror:2 row_mask:0xf bank_mask:0xf
	v_add_f32_dpp v207, v207, v207 row_ror:2 row_mask:0xf bank_mask:0xf
	v_add_f32_dpp v202, v202, v202 row_ror:1 row_mask:0xf bank_mask:0xf
	v_add_f32_dpp v203, v203, v203 row_ror:1 row_mask:0xf bank_mask:0xf
	v_add_f32_dpp v204, v204, v204 row_ror:1 row_mask:0xf bank_mask:0xf
	v_add_f32_dpp v205, v205, v205 row_ror:1 row_mask:0xf bank_mask:0xf
	v_add_f32_dpp v206, v206, v206 row_ror:1 row_mask:0xf bank_mask:0xf
	v_add_f32_dpp v207, v207, v207 row_ror:1 row_mask:0xf bank_mask:0xf
	v_mov_b32_e32 v208, v202
	v_mov_b32_e32 v209, v203
	v_mov_b32_e32 v210, v204
	v_mov_b32_e32 v211, v205
	v_mov_b32_e32 v212, v206
	v_mov_b32_e32 v213, v207
	s_nop 1
	v_permlane16_swap_b32_e32 v208, v202
	v_permlane16_swap_b32_e32 v209, v203
	v_permlane16_swap_b32_e32 v210, v204
	v_permlane16_swap_b32_e32 v211, v205
	v_permlane16_swap_b32_e32 v212, v206
	v_permlane16_swap_b32_e32 v213, v207
	v_add_f32_e32 v202, v202, v208
	v_add_f32_e32 v203, v203, v209
	v_add_f32_e32 v204, v204, v210
	v_add_f32_e32 v205, v205, v211
	v_add_f32_e32 v206, v206, v212
	v_add_f32_e32 v207, v207, v213
	v_mov_b32_e32 v208, v202
	v_mov_b32_e32 v209, v203
	v_mov_b32_e32 v210, v204
	v_mov_b32_e32 v211, v205
	v_mov_b32_e32 v212, v206
	v_mov_b32_e32 v213, v207
	s_nop 1
	v_permlane32_swap_b32_e32 v208, v202
	v_permlane32_swap_b32_e32 v209, v203
	v_permlane32_swap_b32_e32 v210, v204
	v_permlane32_swap_b32_e32 v211, v205
	v_permlane32_swap_b32_e32 v212, v206
	v_permlane32_swap_b32_e32 v213, v207
	v_add_f32_e32 v202, v202, v208
	v_add_f32_e32 v203, v203, v209
	v_add_f32_e32 v204, v204, v210
	v_add_f32_e32 v205, v205, v211
	v_add_f32_e32 v206, v206, v212
	v_add_f32_e32 v207, v207, v213
	v_fma_f32 v202, v202, s28, v167
	v_fma_f32 v203, v203, s28, v167
	v_fma_f32 v204, v204, s28, v167
	v_fma_f32 v205, v205, s28, v167
	v_fma_f32 v206, v206, s28, v167
	v_fma_f32 v207, v207, s28, v167
	v_rsq_f32_e32 v202, v202
	v_rsq_f32_e32 v203, v203
	v_rsq_f32_e32 v204, v204
	v_rsq_f32_e32 v205, v205
	v_rsq_f32_e32 v206, v206
	v_rsq_f32_e32 v207, v207
	s_waitcnt vmcnt(0)
	v_add_f32_e32 v170, 1.0, v170
	v_add_f32_e32 v171, 1.0, v171
	v_add_f32_e32 v172, 1.0, v172
	v_add_f32_e32 v173, 1.0, v173
	v_add_f32_e32 v174, 1.0, v174
	v_add_f32_e32 v175, 1.0, v175
	v_add_f32_e32 v176, 1.0, v176
	v_add_f32_e32 v177, 1.0, v177
	v_add_f32_e32 v178, 1.0, v178
	v_add_f32_e32 v179, 1.0, v179
	v_add_f32_e32 v180, 1.0, v180
	v_add_f32_e32 v181, 1.0, v181
	v_add_f32_e32 v182, 1.0, v182
	v_add_f32_e32 v183, 1.0, v183
	v_add_f32_e32 v184, 1.0, v184
	v_add_f32_e32 v185, 1.0, v185
	v_mul_f32_e32 v170, v148, v170
	v_mul_f32_e32 v171, v149, v171
	v_mul_f32_e32 v172, v150, v172
	v_mul_f32_e32 v173, v151, v173
	v_mul_f32_e32 v174, v152, v174
	v_mul_f32_e32 v175, v153, v175
	v_mul_f32_e32 v176, v154, v176
	v_mul_f32_e32 v177, v155, v177
	v_mul_f32_e32 v178, v156, v178
	v_mul_f32_e32 v179, v157, v179
	v_mul_f32_e32 v180, v158, v180
	v_mul_f32_e32 v181, v159, v181
	v_mul_f32_e32 v182, v160, v182
	v_mul_f32_e32 v183, v161, v183
	v_mul_f32_e32 v184, v162, v184
	v_mul_f32_e32 v185, v163, v185
	v_mul_f32_e32 v2, v2, v202
	v_mul_f32_e32 v3, v3, v202
	v_mul_f32_e32 v4, v4, v202
	v_mul_f32_e32 v5, v5, v202
	v_mul_f32_e32 v6, v6, v202
	v_mul_f32_e32 v7, v7, v202
	v_mul_f32_e32 v8, v8, v202
	v_mul_f32_e32 v9, v9, v202
	v_mul_f32_e32 v10, v10, v202
	v_mul_f32_e32 v11, v11, v202
	v_mul_f32_e32 v12, v12, v202
	v_mul_f32_e32 v13, v13, v202
	v_mul_f32_e32 v14, v14, v202
	v_mul_f32_e32 v15, v15, v202
	v_mul_f32_e32 v16, v16, v202
	v_mul_f32_e32 v17, v17, v202
	v_fma_f32 v2, v2, v170, v186
	v_fma_f32 v3, v3, v171, v187
	v_fma_f32 v4, v4, v172, v188
	v_fma_f32 v5, v5, v173, v189
	v_fma_f32 v6, v6, v174, v190
	v_fma_f32 v7, v7, v175, v191
	v_fma_f32 v8, v8, v176, v192
	v_fma_f32 v9, v9, v177, v193
	v_fma_f32 v10, v10, v178, v194
	v_fma_f32 v11, v11, v179, v195
	v_fma_f32 v12, v12, v180, v196
	v_fma_f32 v13, v13, v181, v197
	v_fma_f32 v14, v14, v182, v198
	v_fma_f32 v15, v15, v183, v199
	v_fma_f32 v16, v16, v184, v200
	v_fma_f32 v17, v17, v185, v201
	s_cmp_lg_u32 s2, 1
	s_cbranch_scc1 .Lnrm_sc1
	s_add_u32 s20, s20, 0x9000
	s_addc_u32 s21, s21, 0
	s_add_u32 s26, s20, 0x1000
	s_addc_u32 s27, s21, 0
	global_load_dwordx4 v[148:151], v82, s[12:13] offset:0
	global_load_dwordx4 v[170:173], v82, s[26:27] offset:0
	global_load_dwordx4 v[186:189], v82, s[20:21] offset:0
	global_load_dwordx4 v[152:155], v82, s[12:13] offset:16
	global_load_dwordx4 v[174:177], v82, s[26:27] offset:16
	global_load_dwordx4 v[190:193], v82, s[20:21] offset:16
	global_load_dwordx4 v[156:159], v82, s[12:13] offset:2048
	global_load_dwordx4 v[178:181], v82, s[26:27] offset:2048
	global_load_dwordx4 v[194:197], v82, s[20:21] offset:2048
	global_load_dwordx4 v[160:163], v82, s[12:13] offset:2064
	global_load_dwordx4 v[182:185], v82, s[26:27] offset:2064
	global_load_dwordx4 v[198:201], v82, s[20:21] offset:2064
	s_waitcnt vmcnt(0)
	v_add_f32_e32 v170, 1.0, v170
	v_add_f32_e32 v171, 1.0, v171
	v_add_f32_e32 v172, 1.0, v172
	v_add_f32_e32 v173, 1.0, v173
	v_add_f32_e32 v174, 1.0, v174
	v_add_f32_e32 v175, 1.0, v175
	v_add_f32_e32 v176, 1.0, v176
	v_add_f32_e32 v177, 1.0, v177
	v_add_f32_e32 v178, 1.0, v178
	v_add_f32_e32 v179, 1.0, v179
	v_add_f32_e32 v180, 1.0, v180
	v_add_f32_e32 v181, 1.0, v181
	v_add_f32_e32 v182, 1.0, v182
	v_add_f32_e32 v183, 1.0, v183
	v_add_f32_e32 v184, 1.0, v184
	v_add_f32_e32 v185, 1.0, v185
	v_mul_f32_e32 v170, v148, v170
	v_mul_f32_e32 v171, v149, v171
	v_mul_f32_e32 v172, v150, v172
	v_mul_f32_e32 v173, v151, v173
	v_mul_f32_e32 v174, v152, v174
	v_mul_f32_e32 v175, v153, v175
	v_mul_f32_e32 v176, v154, v176
	v_mul_f32_e32 v177, v155, v177
	v_mul_f32_e32 v178, v156, v178
	v_mul_f32_e32 v179, v157, v179
	v_mul_f32_e32 v180, v158, v180
	v_mul_f32_e32 v181, v159, v181
	v_mul_f32_e32 v182, v160, v182
	v_mul_f32_e32 v183, v161, v183
	v_mul_f32_e32 v184, v162, v184
	v_mul_f32_e32 v185, v163, v185
.Lnrm_sc1:
	v_mul_f32_e32 v18, v18, v203
	v_mul_f32_e32 v19, v19, v203
	v_mul_f32_e32 v20, v20, v203
	v_mul_f32_e32 v21, v21, v203
	v_mul_f32_e32 v22, v22, v203
	v_mul_f32_e32 v23, v23, v203
	v_mul_f32_e32 v24, v24, v203
	v_mul_f32_e32 v25, v25, v203
	v_mul_f32_e32 v26, v26, v203
	v_mul_f32_e32 v27, v27, v203
	v_mul_f32_e32 v28, v28, v203
	v_mul_f32_e32 v29, v29, v203
	v_mul_f32_e32 v30, v30, v203
	v_mul_f32_e32 v31, v31, v203
	v_mul_f32_e32 v32, v32, v203
	v_mul_f32_e32 v33, v33, v203
	v_fma_f32 v18, v18, v170, v186
	v_fma_f32 v19, v19, v171, v187
	v_fma_f32 v20, v20, v172, v188
	v_fma_f32 v21, v21, v173, v189
	v_fma_f32 v22, v22, v174, v190
	v_fma_f32 v23, v23, v175, v191
	v_fma_f32 v24, v24, v176, v192
	v_fma_f32 v25, v25, v177, v193
	v_fma_f32 v26, v26, v178, v194
	v_fma_f32 v27, v27, v179, v195
	v_fma_f32 v28, v28, v180, v196
	v_fma_f32 v29, v29, v181, v197
	v_fma_f32 v30, v30, v182, v198
	v_fma_f32 v31, v31, v183, v199
	v_fma_f32 v32, v32, v184, v200
	v_fma_f32 v33, v33, v185, v201
	s_cmp_lg_u32 s2, 2
	s_cbranch_scc1 .Lnrm_sc2
	s_add_u32 s20, s20, 0x9000
	s_addc_u32 s21, s21, 0
	s_add_u32 s26, s20, 0x1000
	s_addc_u32 s27, s21, 0
	global_load_dwordx4 v[148:151], v82, s[12:13] offset:0
	global_load_dwordx4 v[170:173], v82, s[26:27] offset:0
	global_load_dwordx4 v[186:189], v82, s[20:21] offset:0
	global_load_dwordx4 v[152:155], v82, s[12:13] offset:16
	global_load_dwordx4 v[174:177], v82, s[26:27] offset:16
	global_load_dwordx4 v[190:193], v82, s[20:21] offset:16
	global_load_dwordx4 v[156:159], v82, s[12:13] offset:2048
	global_load_dwordx4 v[178:181], v82, s[26:27] offset:2048
	global_load_dwordx4 v[194:197], v82, s[20:21] offset:2048
	global_load_dwordx4 v[160:163], v82, s[12:13] offset:2064
	global_load_dwordx4 v[182:185], v82, s[26:27] offset:2064
	global_load_dwordx4 v[198:201], v82, s[20:21] offset:2064
	s_waitcnt vmcnt(0)
	v_add_f32_e32 v170, 1.0, v170
	v_add_f32_e32 v171, 1.0, v171
	v_add_f32_e32 v172, 1.0, v172
	v_add_f32_e32 v173, 1.0, v173
	v_add_f32_e32 v174, 1.0, v174
	v_add_f32_e32 v175, 1.0, v175
	v_add_f32_e32 v176, 1.0, v176
	v_add_f32_e32 v177, 1.0, v177
	v_add_f32_e32 v178, 1.0, v178
	v_add_f32_e32 v179, 1.0, v179
	v_add_f32_e32 v180, 1.0, v180
	v_add_f32_e32 v181, 1.0, v181
	v_add_f32_e32 v182, 1.0, v182
	v_add_f32_e32 v183, 1.0, v183
	v_add_f32_e32 v184, 1.0, v184
	v_add_f32_e32 v185, 1.0, v185
	v_mul_f32_e32 v170, v148, v170
	v_mul_f32_e32 v171, v149, v171
	v_mul_f32_e32 v172, v150, v172
	v_mul_f32_e32 v173, v151, v173
	v_mul_f32_e32 v174, v152, v174
	v_mul_f32_e32 v175, v153, v175
	v_mul_f32_e32 v176, v154, v176
	v_mul_f32_e32 v177, v155, v177
	v_mul_f32_e32 v178, v156, v178
	v_mul_f32_e32 v179, v157, v179
	v_mul_f32_e32 v180, v158, v180
	v_mul_f32_e32 v181, v159, v181
	v_mul_f32_e32 v182, v160, v182
	v_mul_f32_e32 v183, v161, v183
	v_mul_f32_e32 v184, v162, v184
	v_mul_f32_e32 v185, v163, v185
.Lnrm_sc2:
	v_mul_f32_e32 v34, v34, v204
	v_mul_f32_e32 v35, v35, v204
	v_mul_f32_e32 v36, v36, v204
	v_mul_f32_e32 v37, v37, v204
	v_mul_f32_e32 v38, v38, v204
	v_mul_f32_e32 v39, v39, v204
	v_mul_f32_e32 v40, v40, v204
	v_mul_f32_e32 v41, v41, v204
	v_mul_f32_e32 v42, v42, v204
	v_mul_f32_e32 v43, v43, v204
	v_mul_f32_e32 v44, v44, v204
	v_mul_f32_e32 v45, v45, v204
	v_mul_f32_e32 v46, v46, v204
	v_mul_f32_e32 v47, v47, v204
	v_mul_f32_e32 v48, v48, v204
	v_mul_f32_e32 v49, v49, v204
	v_fma_f32 v34, v34, v170, v186
	v_fma_f32 v35, v35, v171, v187
	v_fma_f32 v36, v36, v172, v188
	v_fma_f32 v37, v37, v173, v189
	v_fma_f32 v38, v38, v174, v190
	v_fma_f32 v39, v39, v175, v191
	v_fma_f32 v40, v40, v176, v192
	v_fma_f32 v41, v41, v177, v193
	v_fma_f32 v42, v42, v178, v194
	v_fma_f32 v43, v43, v179, v195
	v_fma_f32 v44, v44, v180, v196
	v_fma_f32 v45, v45, v181, v197
	v_fma_f32 v46, v46, v182, v198
	v_fma_f32 v47, v47, v183, v199
	v_fma_f32 v48, v48, v184, v200
	v_fma_f32 v49, v49, v185, v201
	s_cmp_lg_u32 s2, 3
	s_cbranch_scc1 .Lnrm_sc3
	s_add_u32 s20, s20, 0x9000
	s_addc_u32 s21, s21, 0
	s_add_u32 s26, s20, 0x1000
	s_addc_u32 s27, s21, 0
	global_load_dwordx4 v[148:151], v82, s[12:13] offset:0
	global_load_dwordx4 v[170:173], v82, s[26:27] offset:0
	global_load_dwordx4 v[186:189], v82, s[20:21] offset:0
	global_load_dwordx4 v[152:155], v82, s[12:13] offset:16
	global_load_dwordx4 v[174:177], v82, s[26:27] offset:16
	global_load_dwordx4 v[190:193], v82, s[20:21] offset:16
	global_load_dwordx4 v[156:159], v82, s[12:13] offset:2048
	global_load_dwordx4 v[178:181], v82, s[26:27] offset:2048
	global_load_dwordx4 v[194:197], v82, s[20:21] offset:2048
	global_load_dwordx4 v[160:163], v82, s[12:13] offset:2064
	global_load_dwordx4 v[182:185], v82, s[26:27] offset:2064
	global_load_dwordx4 v[198:201], v82, s[20:21] offset:2064
	s_waitcnt vmcnt(0)
	v_add_f32_e32 v170, 1.0, v170
	v_add_f32_e32 v171, 1.0, v171
	v_add_f32_e32 v172, 1.0, v172
	v_add_f32_e32 v173, 1.0, v173
	v_add_f32_e32 v174, 1.0, v174
	v_add_f32_e32 v175, 1.0, v175
	v_add_f32_e32 v176, 1.0, v176
	v_add_f32_e32 v177, 1.0, v177
	v_add_f32_e32 v178, 1.0, v178
	v_add_f32_e32 v179, 1.0, v179
	v_add_f32_e32 v180, 1.0, v180
	v_add_f32_e32 v181, 1.0, v181
	v_add_f32_e32 v182, 1.0, v182
	v_add_f32_e32 v183, 1.0, v183
	v_add_f32_e32 v184, 1.0, v184
	v_add_f32_e32 v185, 1.0, v185
	v_mul_f32_e32 v170, v148, v170
	v_mul_f32_e32 v171, v149, v171
	v_mul_f32_e32 v172, v150, v172
	v_mul_f32_e32 v173, v151, v173
	v_mul_f32_e32 v174, v152, v174
	v_mul_f32_e32 v175, v153, v175
	v_mul_f32_e32 v176, v154, v176
	v_mul_f32_e32 v177, v155, v177
	v_mul_f32_e32 v178, v156, v178
	v_mul_f32_e32 v179, v157, v179
	v_mul_f32_e32 v180, v158, v180
	v_mul_f32_e32 v181, v159, v181
	v_mul_f32_e32 v182, v160, v182
	v_mul_f32_e32 v183, v161, v183
	v_mul_f32_e32 v184, v162, v184
	v_mul_f32_e32 v185, v163, v185
.Lnrm_sc3:
	v_mul_f32_e32 v50, v50, v205
	v_mul_f32_e32 v51, v51, v205
	v_mul_f32_e32 v52, v52, v205
	v_mul_f32_e32 v53, v53, v205
	v_mul_f32_e32 v54, v54, v205
	v_mul_f32_e32 v55, v55, v205
	v_mul_f32_e32 v56, v56, v205
	v_mul_f32_e32 v57, v57, v205
	v_mul_f32_e32 v58, v58, v205
	v_mul_f32_e32 v59, v59, v205
	v_mul_f32_e32 v60, v60, v205
	v_mul_f32_e32 v61, v61, v205
	v_mul_f32_e32 v62, v62, v205
	v_mul_f32_e32 v63, v63, v205
	v_mul_f32_e32 v64, v64, v205
	v_mul_f32_e32 v65, v65, v205
	v_fma_f32 v50, v50, v170, v186
	v_fma_f32 v51, v51, v171, v187
	v_fma_f32 v52, v52, v172, v188
	v_fma_f32 v53, v53, v173, v189
	v_fma_f32 v54, v54, v174, v190
	v_fma_f32 v55, v55, v175, v191
	v_fma_f32 v56, v56, v176, v192
	v_fma_f32 v57, v57, v177, v193
	v_fma_f32 v58, v58, v178, v194
	v_fma_f32 v59, v59, v179, v195
	v_fma_f32 v60, v60, v180, v196
	v_fma_f32 v61, v61, v181, v197
	v_fma_f32 v62, v62, v182, v198
	v_fma_f32 v63, v63, v183, v199
	v_fma_f32 v64, v64, v184, v200
	v_fma_f32 v65, v65, v185, v201
	s_cmp_lg_u32 s2, 4
	s_cbranch_scc1 .Lnrm_sc4
	s_add_u32 s20, s20, 0x9000
	s_addc_u32 s21, s21, 0
	s_add_u32 s26, s20, 0x1000
	s_addc_u32 s27, s21, 0
	global_load_dwordx4 v[148:151], v82, s[12:13] offset:0
	global_load_dwordx4 v[170:173], v82, s[26:27] offset:0
	global_load_dwordx4 v[186:189], v82, s[20:21] offset:0
	global_load_dwordx4 v[152:155], v82, s[12:13] offset:16
	global_load_dwordx4 v[174:177], v82, s[26:27] offset:16
	global_load_dwordx4 v[190:193], v82, s[20:21] offset:16
	global_load_dwordx4 v[156:159], v82, s[12:13] offset:2048
	global_load_dwordx4 v[178:181], v82, s[26:27] offset:2048
	global_load_dwordx4 v[194:197], v82, s[20:21] offset:2048
	global_load_dwordx4 v[160:163], v82, s[12:13] offset:2064
	global_load_dwordx4 v[182:185], v82, s[26:27] offset:2064
	global_load_dwordx4 v[198:201], v82, s[20:21] offset:2064
	s_waitcnt vmcnt(0)
	v_add_f32_e32 v170, 1.0, v170
	v_add_f32_e32 v171, 1.0, v171
	v_add_f32_e32 v172, 1.0, v172
	v_add_f32_e32 v173, 1.0, v173
	v_add_f32_e32 v174, 1.0, v174
	v_add_f32_e32 v175, 1.0, v175
	v_add_f32_e32 v176, 1.0, v176
	v_add_f32_e32 v177, 1.0, v177
	v_add_f32_e32 v178, 1.0, v178
	v_add_f32_e32 v179, 1.0, v179
	v_add_f32_e32 v180, 1.0, v180
	v_add_f32_e32 v181, 1.0, v181
	v_add_f32_e32 v182, 1.0, v182
	v_add_f32_e32 v183, 1.0, v183
	v_add_f32_e32 v184, 1.0, v184
	v_add_f32_e32 v185, 1.0, v185
	v_mul_f32_e32 v170, v148, v170
	v_mul_f32_e32 v171, v149, v171
	v_mul_f32_e32 v172, v150, v172
	v_mul_f32_e32 v173, v151, v173
	v_mul_f32_e32 v174, v152, v174
	v_mul_f32_e32 v175, v153, v175
	v_mul_f32_e32 v176, v154, v176
	v_mul_f32_e32 v177, v155, v177
	v_mul_f32_e32 v178, v156, v178
	v_mul_f32_e32 v179, v157, v179
	v_mul_f32_e32 v180, v158, v180
	v_mul_f32_e32 v181, v159, v181
	v_mul_f32_e32 v182, v160, v182
	v_mul_f32_e32 v183, v161, v183
	v_mul_f32_e32 v184, v162, v184
	v_mul_f32_e32 v185, v163, v185
.Lnrm_sc4:
	v_mul_f32_e32 v66, v66, v206
	v_mul_f32_e32 v67, v67, v206
	v_mul_f32_e32 v68, v68, v206
	v_mul_f32_e32 v69, v69, v206
	v_mul_f32_e32 v70, v70, v206
	v_mul_f32_e32 v71, v71, v206
	v_mul_f32_e32 v72, v72, v206
	v_mul_f32_e32 v73, v73, v206
	v_mul_f32_e32 v74, v74, v206
	v_mul_f32_e32 v75, v75, v206
	v_mul_f32_e32 v76, v76, v206
	v_mul_f32_e32 v77, v77, v206
	v_mul_f32_e32 v78, v78, v206
	v_mul_f32_e32 v79, v79, v206
	v_mul_f32_e32 v80, v80, v206
	v_mul_f32_e32 v81, v81, v206
	v_fma_f32 v66, v66, v170, v186
	v_fma_f32 v67, v67, v171, v187
	v_fma_f32 v68, v68, v172, v188
	v_fma_f32 v69, v69, v173, v189
	v_fma_f32 v70, v70, v174, v190
	v_fma_f32 v71, v71, v175, v191
	v_fma_f32 v72, v72, v176, v192
	v_fma_f32 v73, v73, v177, v193
	v_fma_f32 v74, v74, v178, v194
	v_fma_f32 v75, v75, v179, v195
	v_fma_f32 v76, v76, v180, v196
	v_fma_f32 v77, v77, v181, v197
	v_fma_f32 v78, v78, v182, v198
	v_fma_f32 v79, v79, v183, v199
	v_fma_f32 v80, v80, v184, v200
	v_fma_f32 v81, v81, v185, v201
	s_cmp_lg_u32 s2, 5
	s_cbranch_scc1 .Lnrm_sc5
	s_add_u32 s20, s20, 0x9000
	s_addc_u32 s21, s21, 0
	s_add_u32 s26, s20, 0x1000
	s_addc_u32 s27, s21, 0
	global_load_dwordx4 v[148:151], v82, s[12:13] offset:0
	global_load_dwordx4 v[170:173], v82, s[26:27] offset:0
	global_load_dwordx4 v[186:189], v82, s[20:21] offset:0
	global_load_dwordx4 v[152:155], v82, s[12:13] offset:16
	global_load_dwordx4 v[174:177], v82, s[26:27] offset:16
	global_load_dwordx4 v[190:193], v82, s[20:21] offset:16
	global_load_dwordx4 v[156:159], v82, s[12:13] offset:2048
	global_load_dwordx4 v[178:181], v82, s[26:27] offset:2048
	global_load_dwordx4 v[194:197], v82, s[20:21] offset:2048
	global_load_dwordx4 v[160:163], v82, s[12:13] offset:2064
	global_load_dwordx4 v[182:185], v82, s[26:27] offset:2064
	global_load_dwordx4 v[198:201], v82, s[20:21] offset:2064
	s_waitcnt vmcnt(0)
	v_add_f32_e32 v170, 1.0, v170
	v_add_f32_e32 v171, 1.0, v171
	v_add_f32_e32 v172, 1.0, v172
	v_add_f32_e32 v173, 1.0, v173
	v_add_f32_e32 v174, 1.0, v174
	v_add_f32_e32 v175, 1.0, v175
	v_add_f32_e32 v176, 1.0, v176
	v_add_f32_e32 v177, 1.0, v177
	v_add_f32_e32 v178, 1.0, v178
	v_add_f32_e32 v179, 1.0, v179
	v_add_f32_e32 v180, 1.0, v180
	v_add_f32_e32 v181, 1.0, v181
	v_add_f32_e32 v182, 1.0, v182
	v_add_f32_e32 v183, 1.0, v183
	v_add_f32_e32 v184, 1.0, v184
	v_add_f32_e32 v185, 1.0, v185
	v_mul_f32_e32 v170, v148, v170
	v_mul_f32_e32 v171, v149, v171
	v_mul_f32_e32 v172, v150, v172
	v_mul_f32_e32 v173, v151, v173
	v_mul_f32_e32 v174, v152, v174
	v_mul_f32_e32 v175, v153, v175
	v_mul_f32_e32 v176, v154, v176
	v_mul_f32_e32 v177, v155, v177
	v_mul_f32_e32 v178, v156, v178
	v_mul_f32_e32 v179, v157, v179
	v_mul_f32_e32 v180, v158, v180
	v_mul_f32_e32 v181, v159, v181
	v_mul_f32_e32 v182, v160, v182
	v_mul_f32_e32 v183, v161, v183
	v_mul_f32_e32 v184, v162, v184
	v_mul_f32_e32 v185, v163, v185
.Lnrm_sc5:
	v_mul_f32_e32 v132, v132, v207
	v_mul_f32_e32 v133, v133, v207
	v_mul_f32_e32 v134, v134, v207
	v_mul_f32_e32 v135, v135, v207
	v_mul_f32_e32 v136, v136, v207
	v_mul_f32_e32 v137, v137, v207
	v_mul_f32_e32 v138, v138, v207
	v_mul_f32_e32 v139, v139, v207
	v_mul_f32_e32 v140, v140, v207
	v_mul_f32_e32 v141, v141, v207
	v_mul_f32_e32 v142, v142, v207
	v_mul_f32_e32 v143, v143, v207
	v_mul_f32_e32 v144, v144, v207
	v_mul_f32_e32 v145, v145, v207
	v_mul_f32_e32 v146, v146, v207
	v_mul_f32_e32 v147, v147, v207
	v_fma_f32 v132, v132, v170, v186
	v_fma_f32 v133, v133, v171, v187
	v_fma_f32 v134, v134, v172, v188
	v_fma_f32 v135, v135, v173, v189
	v_fma_f32 v136, v136, v174, v190
	v_fma_f32 v137, v137, v175, v191
	v_fma_f32 v138, v138, v176, v192
	v_fma_f32 v139, v139, v177, v193
	v_fma_f32 v140, v140, v178, v194
	v_fma_f32 v141, v141, v179, v195
	v_fma_f32 v142, v142, v180, v196
	v_fma_f32 v143, v143, v181, v197
	v_fma_f32 v144, v144, v182, v198
	v_fma_f32 v145, v145, v183, v199
	v_fma_f32 v146, v146, v184, v200
	v_fma_f32 v147, v147, v185, v201
	s_and_b64 vcc, exec, s[56:57]
	s_cbranch_vccz .Lnrm_pack
	v_lshlrev_b32_e32 v84, 8, v92
	v_and_b32_e32 v214, 15, v92
	v_lshrrev_b32_e32 v85, 4, v92
	v_and_b32_e32 v86, 1, v85
	v_lshrrev_b32_e32 v85, 1, v85
	v_lshl_add_u32 v215, v86, 2, v214
	v_lshl_add_u32 v215, v85, 3, v215
	v_min_u32_e32 v217, 15, v215
	v_lshlrev_b32_e32 v217, 2, v217
	global_load_dword v216, v217, s[46:47]
	v_cmp_eq_u32_e64 s[16:17], 1, v214
	v_cmp_eq_u32_e64 s[18:19], 2, v214
	v_cmp_eq_u32_e64 s[22:23], 3, v214
	v_cmp_gt_u32_e64 s[26:27], 4, v214
	v_and_b32_e32 v86, 7, v215
	v_cmp_lt_u32_e64 s[48:49], 3, v86
	s_mov_b64 s[6:7], s[44:45]
	s_add_u32 s8, s44, 0x8000
	s_addc_u32 s9, s45, 0
	s_add_u32 s10, s44, 0x4000
	s_addc_u32 s11, s45, 0
	s_add_u32 s12, s44, 0xc000
	s_addc_u32 s13, s45, 0
	s_mov_b32 s14, 0xbfb8aa3b
	s_mov_b32 s28, 0x3f317218
	v_readlane_b32 s20, v255, 7
	v_readlane_b32 s21, v255, 8
	s_lshl_b64 s[24:25], s[80:81], 6
	s_add_u32 s20, s20, s24
	s_addc_u32 s21, s21, s25
	s_add_u32 s20, s20, 0x200000
	s_addc_u32 s21, s21, 0
	s_waitcnt vmcnt(0)
	v_mov_b32_e32 v148, 0
	v_mov_b32_e32 v149, 0
	v_mov_b32_e32 v150, 0
	v_mov_b32_e32 v151, 0
	v_mov_b32_e32 v152, 0
	v_mov_b32_e32 v153, 0
	v_mov_b32_e32 v154, 0
	v_mov_b32_e32 v155, 0
	v_mov_b32_e32 v156, 0
	v_mov_b32_e32 v157, 0
	v_mov_b32_e32 v158, 0
	v_mov_b32_e32 v159, 0
	v_mov_b32_e32 v160, 0
	v_mov_b32_e32 v161, 0
	v_mov_b32_e32 v162, 0
	v_mov_b32_e32 v163, 0
	v_mov_b32_e32 v170, 0
	v_mov_b32_e32 v171, 0
	v_mov_b32_e32 v172, 0
	v_mov_b32_e32 v173, 0
	v_mov_b32_e32 v174, 0
	v_mov_b32_e32 v175, 0
	v_mov_b32_e32 v176, 0
	v_mov_b32_e32 v177, 0
	v_mov_b32_e32 v178, 0
	v_mov_b32_e32 v179, 0
	v_mov_b32_e32 v180, 0
	v_mov_b32_e32 v181, 0
	v_mov_b32_e32 v182, 0
	v_mov_b32_e32 v183, 0
	v_mov_b32_e32 v184, 0
	v_mov_b32_e32 v185, 0
	v_mov_b32_e32 v186, 0
	v_mov_b32_e32 v187, 0
	v_mov_b32_e32 v188, 0
	v_mov_b32_e32 v189, 0
	v_mov_b32_e32 v190, 0
	v_mov_b32_e32 v191, 0
	v_mov_b32_e32 v192, 0
	v_mov_b32_e32 v193, 0
	v_mov_b32_e32 v194, 0
	v_mov_b32_e32 v195, 0
	v_mov_b32_e32 v196, 0
	v_mov_b32_e32 v197, 0
	v_mov_b32_e32 v198, 0
	v_mov_b32_e32 v199, 0
	v_mov_b32_e32 v200, 0
	v_mov_b32_e32 v201, 0
	global_load_dwordx4 v[94:97], v84, s[6:7] offset:0
	global_load_dwordx4 v[98:101], v84, s[6:7] offset:16
	global_load_dwordx4 v[102:105], v84, s[8:9] offset:0
	global_load_dwordx4 v[106:109], v84, s[8:9] offset:16
	global_load_dwordx4 v[110:113], v84, s[6:7] offset:32
	global_load_dwordx4 v[114:117], v84, s[6:7] offset:48
	global_load_dwordx4 v[118:121], v84, s[8:9] offset:32
	global_load_dwordx4 v[122:125], v84, s[8:9] offset:48
	s_waitcnt vmcnt(4)
	v_fmac_f32_e32 v148, v2, v94
	v_fmac_f32_e32 v149, v2, v95
	v_fmac_f32_e32 v150, v2, v96
	v_fmac_f32_e32 v151, v2, v97
	v_fmac_f32_e32 v152, v2, v98
	v_fmac_f32_e32 v153, v2, v99
	v_fmac_f32_e32 v154, v2, v100
	v_fmac_f32_e32 v155, v2, v101
	v_fmac_f32_e32 v156, v2, v102
	v_fmac_f32_e32 v157, v2, v103
	v_fmac_f32_e32 v158, v2, v104
	v_fmac_f32_e32 v159, v2, v105
	v_fmac_f32_e32 v160, v2, v106
	v_fmac_f32_e32 v161, v2, v107
	v_fmac_f32_e32 v162, v2, v108
	v_fmac_f32_e32 v163, v2, v109
	v_fmac_f32_e32 v170, v18, v94
	v_fmac_f32_e32 v171, v18, v95
	v_fmac_f32_e32 v172, v18, v96
	v_fmac_f32_e32 v173, v18, v97
	v_fmac_f32_e32 v174, v18, v98
	v_fmac_f32_e32 v175, v18, v99
	v_fmac_f32_e32 v176, v18, v100
	v_fmac_f32_e32 v177, v18, v101
	v_fmac_f32_e32 v178, v18, v102
	v_fmac_f32_e32 v179, v18, v103
	v_fmac_f32_e32 v180, v18, v104
	v_fmac_f32_e32 v181, v18, v105
	v_fmac_f32_e32 v182, v18, v106
	v_fmac_f32_e32 v183, v18, v107
	v_fmac_f32_e32 v184, v18, v108
	v_fmac_f32_e32 v185, v18, v109
	v_fmac_f32_e32 v186, v34, v94
	v_fmac_f32_e32 v187, v34, v95
	v_fmac_f32_e32 v188, v34, v96
	v_fmac_f32_e32 v189, v34, v97
	v_fmac_f32_e32 v190, v34, v98
	v_fmac_f32_e32 v191, v34, v99
	v_fmac_f32_e32 v192, v34, v100
	v_fmac_f32_e32 v193, v34, v101
	v_fmac_f32_e32 v194, v34, v102
	v_fmac_f32_e32 v195, v34, v103
	v_fmac_f32_e32 v196, v34, v104
	v_fmac_f32_e32 v197, v34, v105
	v_fmac_f32_e32 v198, v34, v106
	v_fmac_f32_e32 v199, v34, v107
	v_fmac_f32_e32 v200, v34, v108
	v_fmac_f32_e32 v201, v34, v109
	global_load_dwordx4 v[94:97], v84, s[6:7] offset:64
	global_load_dwordx4 v[98:101], v84, s[6:7] offset:80
	global_load_dwordx4 v[102:105], v84, s[8:9] offset:64
	global_load_dwordx4 v[106:109], v84, s[8:9] offset:80
	s_waitcnt vmcnt(4)
	v_fmac_f32_e32 v148, v3, v110
	v_fmac_f32_e32 v149, v3, v111
	v_fmac_f32_e32 v150, v3, v112
	v_fmac_f32_e32 v151, v3, v113
	v_fmac_f32_e32 v152, v3, v114
	v_fmac_f32_e32 v153, v3, v115
	v_fmac_f32_e32 v154, v3, v116
	v_fmac_f32_e32 v155, v3, v117
	v_fmac_f32_e32 v156, v3, v118
	v_fmac_f32_e32 v157, v3, v119
	v_fmac_f32_e32 v158, v3, v120
	v_fmac_f32_e32 v159, v3, v121
	v_fmac_f32_e32 v160, v3, v122
	v_fmac_f32_e32 v161, v3, v123
	v_fmac_f32_e32 v162, v3, v124
	v_fmac_f32_e32 v163, v3, v125
	v_fmac_f32_e32 v170, v19, v110
	v_fmac_f32_e32 v171, v19, v111
	v_fmac_f32_e32 v172, v19, v112
	v_fmac_f32_e32 v173, v19, v113
	v_fmac_f32_e32 v174, v19, v114
	v_fmac_f32_e32 v175, v19, v115
	v_fmac_f32_e32 v176, v19, v116
	v_fmac_f32_e32 v177, v19, v117
	v_fmac_f32_e32 v178, v19, v118
	v_fmac_f32_e32 v179, v19, v119
	v_fmac_f32_e32 v180, v19, v120
	v_fmac_f32_e32 v181, v19, v121
	v_fmac_f32_e32 v182, v19, v122
	v_fmac_f32_e32 v183, v19, v123
	v_fmac_f32_e32 v184, v19, v124
	v_fmac_f32_e32 v185, v19, v125
	v_fmac_f32_e32 v186, v35, v110
	v_fmac_f32_e32 v187, v35, v111
	v_fmac_f32_e32 v188, v35, v112
	v_fmac_f32_e32 v189, v35, v113
	v_fmac_f32_e32 v190, v35, v114
	v_fmac_f32_e32 v191, v35, v115
	v_fmac_f32_e32 v192, v35, v116
	v_fmac_f32_e32 v193, v35, v117
	v_fmac_f32_e32 v194, v35, v118
	v_fmac_f32_e32 v195, v35, v119
	v_fmac_f32_e32 v196, v35, v120
	v_fmac_f32_e32 v197, v35, v121
	v_fmac_f32_e32 v198, v35, v122
	v_fmac_f32_e32 v199, v35, v123
	v_fmac_f32_e32 v200, v35, v124
	v_fmac_f32_e32 v201, v35, v125
	global_load_dwordx4 v[110:113], v84, s[6:7] offset:96
	global_load_dwordx4 v[114:117], v84, s[6:7] offset:112
	global_load_dwordx4 v[118:121], v84, s[8:9] offset:96
	global_load_dwordx4 v[122:125], v84, s[8:9] offset:112
	s_waitcnt vmcnt(4)
	v_fmac_f32_e32 v148, v4, v94
	v_fmac_f32_e32 v149, v4, v95
	v_fmac_f32_e32 v150, v4, v96
	v_fmac_f32_e32 v151, v4, v97
	v_fmac_f32_e32 v152, v4, v98
	v_fmac_f32_e32 v153, v4, v99
	v_fmac_f32_e32 v154, v4, v100
	v_fmac_f32_e32 v155, v4, v101
	v_fmac_f32_e32 v156, v4, v102
	v_fmac_f32_e32 v157, v4, v103
	v_fmac_f32_e32 v158, v4, v104
	v_fmac_f32_e32 v159, v4, v105
	v_fmac_f32_e32 v160, v4, v106
	v_fmac_f32_e32 v161, v4, v107
	v_fmac_f32_e32 v162, v4, v108
	v_fmac_f32_e32 v163, v4, v109
	v_fmac_f32_e32 v170, v20, v94
	v_fmac_f32_e32 v171, v20, v95
	v_fmac_f32_e32 v172, v20, v96
	v_fmac_f32_e32 v173, v20, v97
	v_fmac_f32_e32 v174, v20, v98
	v_fmac_f32_e32 v175, v20, v99
	v_fmac_f32_e32 v176, v20, v100
	v_fmac_f32_e32 v177, v20, v101
	v_fmac_f32_e32 v178, v20, v102
	v_fmac_f32_e32 v179, v20, v103
	v_fmac_f32_e32 v180, v20, v104
	v_fmac_f32_e32 v181, v20, v105
	v_fmac_f32_e32 v182, v20, v106
	v_fmac_f32_e32 v183, v20, v107
	v_fmac_f32_e32 v184, v20, v108
	v_fmac_f32_e32 v185, v20, v109
	v_fmac_f32_e32 v186, v36, v94
	v_fmac_f32_e32 v187, v36, v95
	v_fmac_f32_e32 v188, v36, v96
	v_fmac_f32_e32 v189, v36, v97
	v_fmac_f32_e32 v190, v36, v98
	v_fmac_f32_e32 v191, v36, v99
	v_fmac_f32_e32 v192, v36, v100
	v_fmac_f32_e32 v193, v36, v101
	v_fmac_f32_e32 v194, v36, v102
	v_fmac_f32_e32 v195, v36, v103
	v_fmac_f32_e32 v196, v36, v104
	v_fmac_f32_e32 v197, v36, v105
	v_fmac_f32_e32 v198, v36, v106
	v_fmac_f32_e32 v199, v36, v107
	v_fmac_f32_e32 v200, v36, v108
	v_fmac_f32_e32 v201, v36, v109
	global_load_dwordx4 v[94:97], v84, s[6:7] offset:128
	global_load_dwordx4 v[98:101], v84, s[6:7] offset:144
	global_load_dwordx4 v[102:105], v84, s[8:9] offset:128
	global_load_dwordx4 v[106:109], v84, s[8:9] offset:144
	s_waitcnt vmcnt(4)
	v_fmac_f32_e32 v148, v5, v110
	v_fmac_f32_e32 v149, v5, v111
	v_fmac_f32_e32 v150, v5, v112
	v_fmac_f32_e32 v151, v5, v113
	v_fmac_f32_e32 v152, v5, v114
	v_fmac_f32_e32 v153, v5, v115
	v_fmac_f32_e32 v154, v5, v116
	v_fmac_f32_e32 v155, v5, v117
	v_fmac_f32_e32 v156, v5, v118
	v_fmac_f32_e32 v157, v5, v119
	v_fmac_f32_e32 v158, v5, v120
	v_fmac_f32_e32 v159, v5, v121
	v_fmac_f32_e32 v160, v5, v122
	v_fmac_f32_e32 v161, v5, v123
	v_fmac_f32_e32 v162, v5, v124
	v_fmac_f32_e32 v163, v5, v125
	v_fmac_f32_e32 v170, v21, v110
	v_fmac_f32_e32 v171, v21, v111
	v_fmac_f32_e32 v172, v21, v112
	v_fmac_f32_e32 v173, v21, v113
	v_fmac_f32_e32 v174, v21, v114
	v_fmac_f32_e32 v175, v21, v115
	v_fmac_f32_e32 v176, v21, v116
	v_fmac_f32_e32 v177, v21, v117
	v_fmac_f32_e32 v178, v21, v118
	v_fmac_f32_e32 v179, v21, v119
	v_fmac_f32_e32 v180, v21, v120
	v_fmac_f32_e32 v181, v21, v121
	v_fmac_f32_e32 v182, v21, v122
	v_fmac_f32_e32 v183, v21, v123
	v_fmac_f32_e32 v184, v21, v124
	v_fmac_f32_e32 v185, v21, v125
	v_fmac_f32_e32 v186, v37, v110
	v_fmac_f32_e32 v187, v37, v111
	v_fmac_f32_e32 v188, v37, v112
	v_fmac_f32_e32 v189, v37, v113
	v_fmac_f32_e32 v190, v37, v114
	v_fmac_f32_e32 v191, v37, v115
	v_fmac_f32_e32 v192, v37, v116
	v_fmac_f32_e32 v193, v37, v117
	v_fmac_f32_e32 v194, v37, v118
	v_fmac_f32_e32 v195, v37, v119
	v_fmac_f32_e32 v196, v37, v120
	v_fmac_f32_e32 v197, v37, v121
	v_fmac_f32_e32 v198, v37, v122
	v_fmac_f32_e32 v199, v37, v123
	v_fmac_f32_e32 v200, v37, v124
	v_fmac_f32_e32 v201, v37, v125
	global_load_dwordx4 v[110:113], v84, s[6:7] offset:160
	global_load_dwordx4 v[114:117], v84, s[6:7] offset:176
	global_load_dwordx4 v[118:121], v84, s[8:9] offset:160
	global_load_dwordx4 v[122:125], v84, s[8:9] offset:176
	s_waitcnt vmcnt(4)
	v_fmac_f32_e32 v148, v6, v94
	v_fmac_f32_e32 v149, v6, v95
	v_fmac_f32_e32 v150, v6, v96
	v_fmac_f32_e32 v151, v6, v97
	v_fmac_f32_e32 v152, v6, v98
	v_fmac_f32_e32 v153, v6, v99
	v_fmac_f32_e32 v154, v6, v100
	v_fmac_f32_e32 v155, v6, v101
	v_fmac_f32_e32 v156, v6, v102
	v_fmac_f32_e32 v157, v6, v103
	v_fmac_f32_e32 v158, v6, v104
	v_fmac_f32_e32 v159, v6, v105
	v_fmac_f32_e32 v160, v6, v106
	v_fmac_f32_e32 v161, v6, v107
	v_fmac_f32_e32 v162, v6, v108
	v_fmac_f32_e32 v163, v6, v109
	v_fmac_f32_e32 v170, v22, v94
	v_fmac_f32_e32 v171, v22, v95
	v_fmac_f32_e32 v172, v22, v96
	v_fmac_f32_e32 v173, v22, v97
	v_fmac_f32_e32 v174, v22, v98
	v_fmac_f32_e32 v175, v22, v99
	v_fmac_f32_e32 v176, v22, v100
	v_fmac_f32_e32 v177, v22, v101
	v_fmac_f32_e32 v178, v22, v102
	v_fmac_f32_e32 v179, v22, v103
	v_fmac_f32_e32 v180, v22, v104
	v_fmac_f32_e32 v181, v22, v105
	v_fmac_f32_e32 v182, v22, v106
	v_fmac_f32_e32 v183, v22, v107
	v_fmac_f32_e32 v184, v22, v108
	v_fmac_f32_e32 v185, v22, v109
	v_fmac_f32_e32 v186, v38, v94
	v_fmac_f32_e32 v187, v38, v95
	v_fmac_f32_e32 v188, v38, v96
	v_fmac_f32_e32 v189, v38, v97
	v_fmac_f32_e32 v190, v38, v98
	v_fmac_f32_e32 v191, v38, v99
	v_fmac_f32_e32 v192, v38, v100
	v_fmac_f32_e32 v193, v38, v101
	v_fmac_f32_e32 v194, v38, v102
	v_fmac_f32_e32 v195, v38, v103
	v_fmac_f32_e32 v196, v38, v104
	v_fmac_f32_e32 v197, v38, v105
	v_fmac_f32_e32 v198, v38, v106
	v_fmac_f32_e32 v199, v38, v107
	v_fmac_f32_e32 v200, v38, v108
	v_fmac_f32_e32 v201, v38, v109
	global_load_dwordx4 v[94:97], v84, s[6:7] offset:192
	global_load_dwordx4 v[98:101], v84, s[6:7] offset:208
	global_load_dwordx4 v[102:105], v84, s[8:9] offset:192
	global_load_dwordx4 v[106:109], v84, s[8:9] offset:208
	s_waitcnt vmcnt(4)
	v_fmac_f32_e32 v148, v7, v110
	v_fmac_f32_e32 v149, v7, v111
	v_fmac_f32_e32 v150, v7, v112
	v_fmac_f32_e32 v151, v7, v113
	v_fmac_f32_e32 v152, v7, v114
	v_fmac_f32_e32 v153, v7, v115
	v_fmac_f32_e32 v154, v7, v116
	v_fmac_f32_e32 v155, v7, v117
	v_fmac_f32_e32 v156, v7, v118
	v_fmac_f32_e32 v157, v7, v119
	v_fmac_f32_e32 v158, v7, v120
	v_fmac_f32_e32 v159, v7, v121
	v_fmac_f32_e32 v160, v7, v122
	v_fmac_f32_e32 v161, v7, v123
	v_fmac_f32_e32 v162, v7, v124
	v_fmac_f32_e32 v163, v7, v125
	v_fmac_f32_e32 v170, v23, v110
	v_fmac_f32_e32 v171, v23, v111
	v_fmac_f32_e32 v172, v23, v112
	v_fmac_f32_e32 v173, v23, v113
	v_fmac_f32_e32 v174, v23, v114
	v_fmac_f32_e32 v175, v23, v115
	v_fmac_f32_e32 v176, v23, v116
	v_fmac_f32_e32 v177, v23, v117
	v_fmac_f32_e32 v178, v23, v118
	v_fmac_f32_e32 v179, v23, v119
	v_fmac_f32_e32 v180, v23, v120
	v_fmac_f32_e32 v181, v23, v121
	v_fmac_f32_e32 v182, v23, v122
	v_fmac_f32_e32 v183, v23, v123
	v_fmac_f32_e32 v184, v23, v124
	v_fmac_f32_e32 v185, v23, v125
	v_fmac_f32_e32 v186, v39, v110
	v_fmac_f32_e32 v187, v39, v111
	v_fmac_f32_e32 v188, v39, v112
	v_fmac_f32_e32 v189, v39, v113
	v_fmac_f32_e32 v190, v39, v114
	v_fmac_f32_e32 v191, v39, v115
	v_fmac_f32_e32 v192, v39, v116
	v_fmac_f32_e32 v193, v39, v117
	v_fmac_f32_e32 v194, v39, v118
	v_fmac_f32_e32 v195, v39, v119
	v_fmac_f32_e32 v196, v39, v120
	v_fmac_f32_e32 v197, v39, v121
	v_fmac_f32_e32 v198, v39, v122
	v_fmac_f32_e32 v199, v39, v123
	v_fmac_f32_e32 v200, v39, v124
	v_fmac_f32_e32 v201, v39, v125
	global_load_dwordx4 v[110:113], v84, s[6:7] offset:224
	global_load_dwordx4 v[114:117], v84, s[6:7] offset:240
	global_load_dwordx4 v[118:121], v84, s[8:9] offset:224
	global_load_dwordx4 v[122:125], v84, s[8:9] offset:240
	s_waitcnt vmcnt(4)
	v_fmac_f32_e32 v148, v8, v94
	v_fmac_f32_e32 v149, v8, v95
	v_fmac_f32_e32 v150, v8, v96
	v_fmac_f32_e32 v151, v8, v97
	v_fmac_f32_e32 v152, v8, v98
	v_fmac_f32_e32 v153, v8, v99
	v_fmac_f32_e32 v154, v8, v100
	v_fmac_f32_e32 v155, v8, v101
	v_fmac_f32_e32 v156, v8, v102
	v_fmac_f32_e32 v157, v8, v103
	v_fmac_f32_e32 v158, v8, v104
	v_fmac_f32_e32 v159, v8, v105
	v_fmac_f32_e32 v160, v8, v106
	v_fmac_f32_e32 v161, v8, v107
	v_fmac_f32_e32 v162, v8, v108
	v_fmac_f32_e32 v163, v8, v109
	v_fmac_f32_e32 v170, v24, v94
	v_fmac_f32_e32 v171, v24, v95
	v_fmac_f32_e32 v172, v24, v96
	v_fmac_f32_e32 v173, v24, v97
	v_fmac_f32_e32 v174, v24, v98
	v_fmac_f32_e32 v175, v24, v99
	v_fmac_f32_e32 v176, v24, v100
	v_fmac_f32_e32 v177, v24, v101
	v_fmac_f32_e32 v178, v24, v102
	v_fmac_f32_e32 v179, v24, v103
	v_fmac_f32_e32 v180, v24, v104
	v_fmac_f32_e32 v181, v24, v105
	v_fmac_f32_e32 v182, v24, v106
	v_fmac_f32_e32 v183, v24, v107
	v_fmac_f32_e32 v184, v24, v108
	v_fmac_f32_e32 v185, v24, v109
	v_fmac_f32_e32 v186, v40, v94
	v_fmac_f32_e32 v187, v40, v95
	v_fmac_f32_e32 v188, v40, v96
	v_fmac_f32_e32 v189, v40, v97
	v_fmac_f32_e32 v190, v40, v98
	v_fmac_f32_e32 v191, v40, v99
	v_fmac_f32_e32 v192, v40, v100
	v_fmac_f32_e32 v193, v40, v101
	v_fmac_f32_e32 v194, v40, v102
	v_fmac_f32_e32 v195, v40, v103
	v_fmac_f32_e32 v196, v40, v104
	v_fmac_f32_e32 v197, v40, v105
	v_fmac_f32_e32 v198, v40, v106
	v_fmac_f32_e32 v199, v40, v107
	v_fmac_f32_e32 v200, v40, v108
	v_fmac_f32_e32 v201, v40, v109
	global_load_dwordx4 v[94:97], v84, s[10:11] offset:0
	global_load_dwordx4 v[98:101], v84, s[10:11] offset:16
	global_load_dwordx4 v[102:105], v84, s[12:13] offset:0
	global_load_dwordx4 v[106:109], v84, s[12:13] offset:16
	s_waitcnt vmcnt(4)
	v_fmac_f32_e32 v148, v9, v110
	v_fmac_f32_e32 v149, v9, v111
	v_fmac_f32_e32 v150, v9, v112
	v_fmac_f32_e32 v151, v9, v113
	v_fmac_f32_e32 v152, v9, v114
	v_fmac_f32_e32 v153, v9, v115
	v_fmac_f32_e32 v154, v9, v116
	v_fmac_f32_e32 v155, v9, v117
	v_fmac_f32_e32 v156, v9, v118
	v_fmac_f32_e32 v157, v9, v119
	v_fmac_f32_e32 v158, v9, v120
	v_fmac_f32_e32 v159, v9, v121
	v_fmac_f32_e32 v160, v9, v122
	v_fmac_f32_e32 v161, v9, v123
	v_fmac_f32_e32 v162, v9, v124
	v_fmac_f32_e32 v163, v9, v125
	v_fmac_f32_e32 v170, v25, v110
	v_fmac_f32_e32 v171, v25, v111
	v_fmac_f32_e32 v172, v25, v112
	v_fmac_f32_e32 v173, v25, v113
	v_fmac_f32_e32 v174, v25, v114
	v_fmac_f32_e32 v175, v25, v115
	v_fmac_f32_e32 v176, v25, v116
	v_fmac_f32_e32 v177, v25, v117
	v_fmac_f32_e32 v178, v25, v118
	v_fmac_f32_e32 v179, v25, v119
	v_fmac_f32_e32 v180, v25, v120
	v_fmac_f32_e32 v181, v25, v121
	v_fmac_f32_e32 v182, v25, v122
	v_fmac_f32_e32 v183, v25, v123
	v_fmac_f32_e32 v184, v25, v124
	v_fmac_f32_e32 v185, v25, v125
	v_fmac_f32_e32 v186, v41, v110
	v_fmac_f32_e32 v187, v41, v111
	v_fmac_f32_e32 v188, v41, v112
	v_fmac_f32_e32 v189, v41, v113
	v_fmac_f32_e32 v190, v41, v114
	v_fmac_f32_e32 v191, v41, v115
	v_fmac_f32_e32 v192, v41, v116
	v_fmac_f32_e32 v193, v41, v117
	v_fmac_f32_e32 v194, v41, v118
	v_fmac_f32_e32 v195, v41, v119
	v_fmac_f32_e32 v196, v41, v120
	v_fmac_f32_e32 v197, v41, v121
	v_fmac_f32_e32 v198, v41, v122
	v_fmac_f32_e32 v199, v41, v123
	v_fmac_f32_e32 v200, v41, v124
	v_fmac_f32_e32 v201, v41, v125
	global_load_dwordx4 v[110:113], v84, s[10:11] offset:32
	global_load_dwordx4 v[114:117], v84, s[10:11] offset:48
	global_load_dwordx4 v[118:121], v84, s[12:13] offset:32
	global_load_dwordx4 v[122:125], v84, s[12:13] offset:48
	s_waitcnt vmcnt(4)
	v_fmac_f32_e32 v148, v10, v94
	v_fmac_f32_e32 v149, v10, v95
	v_fmac_f32_e32 v150, v10, v96
	v_fmac_f32_e32 v151, v10, v97
	v_fmac_f32_e32 v152, v10, v98
	v_fmac_f32_e32 v153, v10, v99
	v_fmac_f32_e32 v154, v10, v100
	v_fmac_f32_e32 v155, v10, v101
	v_fmac_f32_e32 v156, v10, v102
	v_fmac_f32_e32 v157, v10, v103
	v_fmac_f32_e32 v158, v10, v104
	v_fmac_f32_e32 v159, v10, v105
	v_fmac_f32_e32 v160, v10, v106
	v_fmac_f32_e32 v161, v10, v107
	v_fmac_f32_e32 v162, v10, v108
	v_fmac_f32_e32 v163, v10, v109
	v_fmac_f32_e32 v170, v26, v94
	v_fmac_f32_e32 v171, v26, v95
	v_fmac_f32_e32 v172, v26, v96
	v_fmac_f32_e32 v173, v26, v97
	v_fmac_f32_e32 v174, v26, v98
	v_fmac_f32_e32 v175, v26, v99
	v_fmac_f32_e32 v176, v26, v100
	v_fmac_f32_e32 v177, v26, v101
	v_fmac_f32_e32 v178, v26, v102
	v_fmac_f32_e32 v179, v26, v103
	v_fmac_f32_e32 v180, v26, v104
	v_fmac_f32_e32 v181, v26, v105
	v_fmac_f32_e32 v182, v26, v106
	v_fmac_f32_e32 v183, v26, v107
	v_fmac_f32_e32 v184, v26, v108
	v_fmac_f32_e32 v185, v26, v109
	v_fmac_f32_e32 v186, v42, v94
	v_fmac_f32_e32 v187, v42, v95
	v_fmac_f32_e32 v188, v42, v96
	v_fmac_f32_e32 v189, v42, v97
	v_fmac_f32_e32 v190, v42, v98
	v_fmac_f32_e32 v191, v42, v99
	v_fmac_f32_e32 v192, v42, v100
	v_fmac_f32_e32 v193, v42, v101
	v_fmac_f32_e32 v194, v42, v102
	v_fmac_f32_e32 v195, v42, v103
	v_fmac_f32_e32 v196, v42, v104
	v_fmac_f32_e32 v197, v42, v105
	v_fmac_f32_e32 v198, v42, v106
	v_fmac_f32_e32 v199, v42, v107
	v_fmac_f32_e32 v200, v42, v108
	v_fmac_f32_e32 v201, v42, v109
	global_load_dwordx4 v[94:97], v84, s[10:11] offset:64
	global_load_dwordx4 v[98:101], v84, s[10:11] offset:80
	global_load_dwordx4 v[102:105], v84, s[12:13] offset:64
	global_load_dwordx4 v[106:109], v84, s[12:13] offset:80
	s_waitcnt vmcnt(4)
	v_fmac_f32_e32 v148, v11, v110
	v_fmac_f32_e32 v149, v11, v111
	v_fmac_f32_e32 v150, v11, v112
	v_fmac_f32_e32 v151, v11, v113
	v_fmac_f32_e32 v152, v11, v114
	v_fmac_f32_e32 v153, v11, v115
	v_fmac_f32_e32 v154, v11, v116
	v_fmac_f32_e32 v155, v11, v117
	v_fmac_f32_e32 v156, v11, v118
	v_fmac_f32_e32 v157, v11, v119
	v_fmac_f32_e32 v158, v11, v120
	v_fmac_f32_e32 v159, v11, v121
	v_fmac_f32_e32 v160, v11, v122
	v_fmac_f32_e32 v161, v11, v123
	v_fmac_f32_e32 v162, v11, v124
	v_fmac_f32_e32 v163, v11, v125
	v_fmac_f32_e32 v170, v27, v110
	v_fmac_f32_e32 v171, v27, v111
	v_fmac_f32_e32 v172, v27, v112
	v_fmac_f32_e32 v173, v27, v113
	v_fmac_f32_e32 v174, v27, v114
	v_fmac_f32_e32 v175, v27, v115
	v_fmac_f32_e32 v176, v27, v116
	v_fmac_f32_e32 v177, v27, v117
	v_fmac_f32_e32 v178, v27, v118
	v_fmac_f32_e32 v179, v27, v119
	v_fmac_f32_e32 v180, v27, v120
	v_fmac_f32_e32 v181, v27, v121
	v_fmac_f32_e32 v182, v27, v122
	v_fmac_f32_e32 v183, v27, v123
	v_fmac_f32_e32 v184, v27, v124
	v_fmac_f32_e32 v185, v27, v125
	v_fmac_f32_e32 v186, v43, v110
	v_fmac_f32_e32 v187, v43, v111
	v_fmac_f32_e32 v188, v43, v112
	v_fmac_f32_e32 v189, v43, v113
	v_fmac_f32_e32 v190, v43, v114
	v_fmac_f32_e32 v191, v43, v115
	v_fmac_f32_e32 v192, v43, v116
	v_fmac_f32_e32 v193, v43, v117
	v_fmac_f32_e32 v194, v43, v118
	v_fmac_f32_e32 v195, v43, v119
	v_fmac_f32_e32 v196, v43, v120
	v_fmac_f32_e32 v197, v43, v121
	v_fmac_f32_e32 v198, v43, v122
	v_fmac_f32_e32 v199, v43, v123
	v_fmac_f32_e32 v200, v43, v124
	v_fmac_f32_e32 v201, v43, v125
	global_load_dwordx4 v[110:113], v84, s[10:11] offset:96
	global_load_dwordx4 v[114:117], v84, s[10:11] offset:112
	global_load_dwordx4 v[118:121], v84, s[12:13] offset:96
	global_load_dwordx4 v[122:125], v84, s[12:13] offset:112
	s_waitcnt vmcnt(4)
	v_fmac_f32_e32 v148, v12, v94
	v_fmac_f32_e32 v149, v12, v95
	v_fmac_f32_e32 v150, v12, v96
	v_fmac_f32_e32 v151, v12, v97
	v_fmac_f32_e32 v152, v12, v98
	v_fmac_f32_e32 v153, v12, v99
	v_fmac_f32_e32 v154, v12, v100
	v_fmac_f32_e32 v155, v12, v101
	v_fmac_f32_e32 v156, v12, v102
	v_fmac_f32_e32 v157, v12, v103
	v_fmac_f32_e32 v158, v12, v104
	v_fmac_f32_e32 v159, v12, v105
	v_fmac_f32_e32 v160, v12, v106
	v_fmac_f32_e32 v161, v12, v107
	v_fmac_f32_e32 v162, v12, v108
	v_fmac_f32_e32 v163, v12, v109
	v_fmac_f32_e32 v170, v28, v94
	v_fmac_f32_e32 v171, v28, v95
	v_fmac_f32_e32 v172, v28, v96
	v_fmac_f32_e32 v173, v28, v97
	v_fmac_f32_e32 v174, v28, v98
	v_fmac_f32_e32 v175, v28, v99
	v_fmac_f32_e32 v176, v28, v100
	v_fmac_f32_e32 v177, v28, v101
	v_fmac_f32_e32 v178, v28, v102
	v_fmac_f32_e32 v179, v28, v103
	v_fmac_f32_e32 v180, v28, v104
	v_fmac_f32_e32 v181, v28, v105
	v_fmac_f32_e32 v182, v28, v106
	v_fmac_f32_e32 v183, v28, v107
	v_fmac_f32_e32 v184, v28, v108
	v_fmac_f32_e32 v185, v28, v109
	v_fmac_f32_e32 v186, v44, v94
	v_fmac_f32_e32 v187, v44, v95
	v_fmac_f32_e32 v188, v44, v96
	v_fmac_f32_e32 v189, v44, v97
	v_fmac_f32_e32 v190, v44, v98
	v_fmac_f32_e32 v191, v44, v99
	v_fmac_f32_e32 v192, v44, v100
	v_fmac_f32_e32 v193, v44, v101
	v_fmac_f32_e32 v194, v44, v102
	v_fmac_f32_e32 v195, v44, v103
	v_fmac_f32_e32 v196, v44, v104
	v_fmac_f32_e32 v197, v44, v105
	v_fmac_f32_e32 v198, v44, v106
	v_fmac_f32_e32 v199, v44, v107
	v_fmac_f32_e32 v200, v44, v108
	v_fmac_f32_e32 v201, v44, v109
	global_load_dwordx4 v[94:97], v84, s[10:11] offset:128
	global_load_dwordx4 v[98:101], v84, s[10:11] offset:144
	global_load_dwordx4 v[102:105], v84, s[12:13] offset:128
	global_load_dwordx4 v[106:109], v84, s[12:13] offset:144
	s_waitcnt vmcnt(4)
	v_fmac_f32_e32 v148, v13, v110
	v_fmac_f32_e32 v149, v13, v111
	v_fmac_f32_e32 v150, v13, v112
	v_fmac_f32_e32 v151, v13, v113
	v_fmac_f32_e32 v152, v13, v114
	v_fmac_f32_e32 v153, v13, v115
	v_fmac_f32_e32 v154, v13, v116
	v_fmac_f32_e32 v155, v13, v117
	v_fmac_f32_e32 v156, v13, v118
	v_fmac_f32_e32 v157, v13, v119
	v_fmac_f32_e32 v158, v13, v120
	v_fmac_f32_e32 v159, v13, v121
	v_fmac_f32_e32 v160, v13, v122
	v_fmac_f32_e32 v161, v13, v123
	v_fmac_f32_e32 v162, v13, v124
	v_fmac_f32_e32 v163, v13, v125
	v_fmac_f32_e32 v170, v29, v110
	v_fmac_f32_e32 v171, v29, v111
	v_fmac_f32_e32 v172, v29, v112
	v_fmac_f32_e32 v173, v29, v113
	v_fmac_f32_e32 v174, v29, v114
	v_fmac_f32_e32 v175, v29, v115
	v_fmac_f32_e32 v176, v29, v116
	v_fmac_f32_e32 v177, v29, v117
	v_fmac_f32_e32 v178, v29, v118
	v_fmac_f32_e32 v179, v29, v119
	v_fmac_f32_e32 v180, v29, v120
	v_fmac_f32_e32 v181, v29, v121
	v_fmac_f32_e32 v182, v29, v122
	v_fmac_f32_e32 v183, v29, v123
	v_fmac_f32_e32 v184, v29, v124
	v_fmac_f32_e32 v185, v29, v125
	v_fmac_f32_e32 v186, v45, v110
	v_fmac_f32_e32 v187, v45, v111
	v_fmac_f32_e32 v188, v45, v112
	v_fmac_f32_e32 v189, v45, v113
	v_fmac_f32_e32 v190, v45, v114
	v_fmac_f32_e32 v191, v45, v115
	v_fmac_f32_e32 v192, v45, v116
	v_fmac_f32_e32 v193, v45, v117
	v_fmac_f32_e32 v194, v45, v118
	v_fmac_f32_e32 v195, v45, v119
	v_fmac_f32_e32 v196, v45, v120
	v_fmac_f32_e32 v197, v45, v121
	v_fmac_f32_e32 v198, v45, v122
	v_fmac_f32_e32 v199, v45, v123
	v_fmac_f32_e32 v200, v45, v124
	v_fmac_f32_e32 v201, v45, v125
	global_load_dwordx4 v[110:113], v84, s[10:11] offset:160
	global_load_dwordx4 v[114:117], v84, s[10:11] offset:176
	global_load_dwordx4 v[118:121], v84, s[12:13] offset:160
	global_load_dwordx4 v[122:125], v84, s[12:13] offset:176
	s_waitcnt vmcnt(4)
	v_fmac_f32_e32 v148, v14, v94
	v_fmac_f32_e32 v149, v14, v95
	v_fmac_f32_e32 v150, v14, v96
	v_fmac_f32_e32 v151, v14, v97
	v_fmac_f32_e32 v152, v14, v98
	v_fmac_f32_e32 v153, v14, v99
	v_fmac_f32_e32 v154, v14, v100
	v_fmac_f32_e32 v155, v14, v101
	v_fmac_f32_e32 v156, v14, v102
	v_fmac_f32_e32 v157, v14, v103
	v_fmac_f32_e32 v158, v14, v104
	v_fmac_f32_e32 v159, v14, v105
	v_fmac_f32_e32 v160, v14, v106
	v_fmac_f32_e32 v161, v14, v107
	v_fmac_f32_e32 v162, v14, v108
	v_fmac_f32_e32 v163, v14, v109
	v_fmac_f32_e32 v170, v30, v94
	v_fmac_f32_e32 v171, v30, v95
	v_fmac_f32_e32 v172, v30, v96
	v_fmac_f32_e32 v173, v30, v97
	v_fmac_f32_e32 v174, v30, v98
	v_fmac_f32_e32 v175, v30, v99
	v_fmac_f32_e32 v176, v30, v100
	v_fmac_f32_e32 v177, v30, v101
	v_fmac_f32_e32 v178, v30, v102
	v_fmac_f32_e32 v179, v30, v103
	v_fmac_f32_e32 v180, v30, v104
	v_fmac_f32_e32 v181, v30, v105
	v_fmac_f32_e32 v182, v30, v106
	v_fmac_f32_e32 v183, v30, v107
	v_fmac_f32_e32 v184, v30, v108
	v_fmac_f32_e32 v185, v30, v109
	v_fmac_f32_e32 v186, v46, v94
	v_fmac_f32_e32 v187, v46, v95
	v_fmac_f32_e32 v188, v46, v96
	v_fmac_f32_e32 v189, v46, v97
	v_fmac_f32_e32 v190, v46, v98
	v_fmac_f32_e32 v191, v46, v99
	v_fmac_f32_e32 v192, v46, v100
	v_fmac_f32_e32 v193, v46, v101
	v_fmac_f32_e32 v194, v46, v102
	v_fmac_f32_e32 v195, v46, v103
	v_fmac_f32_e32 v196, v46, v104
	v_fmac_f32_e32 v197, v46, v105
	v_fmac_f32_e32 v198, v46, v106
	v_fmac_f32_e32 v199, v46, v107
	v_fmac_f32_e32 v200, v46, v108
	v_fmac_f32_e32 v201, v46, v109
	global_load_dwordx4 v[94:97], v84, s[10:11] offset:192
	global_load_dwordx4 v[98:101], v84, s[10:11] offset:208
	global_load_dwordx4 v[102:105], v84, s[12:13] offset:192
	global_load_dwordx4 v[106:109], v84, s[12:13] offset:208
	s_waitcnt vmcnt(4)
	v_fmac_f32_e32 v148, v15, v110
	v_fmac_f32_e32 v149, v15, v111
	v_fmac_f32_e32 v150, v15, v112
	v_fmac_f32_e32 v151, v15, v113
	v_fmac_f32_e32 v152, v15, v114
	v_fmac_f32_e32 v153, v15, v115
	v_fmac_f32_e32 v154, v15, v116
	v_fmac_f32_e32 v155, v15, v117
	v_fmac_f32_e32 v156, v15, v118
	v_fmac_f32_e32 v157, v15, v119
	v_fmac_f32_e32 v158, v15, v120
	v_fmac_f32_e32 v159, v15, v121
	v_fmac_f32_e32 v160, v15, v122
	v_fmac_f32_e32 v161, v15, v123
	v_fmac_f32_e32 v162, v15, v124
	v_fmac_f32_e32 v163, v15, v125
	v_fmac_f32_e32 v170, v31, v110
	v_fmac_f32_e32 v171, v31, v111
	v_fmac_f32_e32 v172, v31, v112
	v_fmac_f32_e32 v173, v31, v113
	v_fmac_f32_e32 v174, v31, v114
	v_fmac_f32_e32 v175, v31, v115
	v_fmac_f32_e32 v176, v31, v116
	v_fmac_f32_e32 v177, v31, v117
	v_fmac_f32_e32 v178, v31, v118
	v_fmac_f32_e32 v179, v31, v119
	v_fmac_f32_e32 v180, v31, v120
	v_fmac_f32_e32 v181, v31, v121
	v_fmac_f32_e32 v182, v31, v122
	v_fmac_f32_e32 v183, v31, v123
	v_fmac_f32_e32 v184, v31, v124
	v_fmac_f32_e32 v185, v31, v125
	v_fmac_f32_e32 v186, v47, v110
	v_fmac_f32_e32 v187, v47, v111
	v_fmac_f32_e32 v188, v47, v112
	v_fmac_f32_e32 v189, v47, v113
	v_fmac_f32_e32 v190, v47, v114
	v_fmac_f32_e32 v191, v47, v115
	v_fmac_f32_e32 v192, v47, v116
	v_fmac_f32_e32 v193, v47, v117
	v_fmac_f32_e32 v194, v47, v118
	v_fmac_f32_e32 v195, v47, v119
	v_fmac_f32_e32 v196, v47, v120
	v_fmac_f32_e32 v197, v47, v121
	v_fmac_f32_e32 v198, v47, v122
	v_fmac_f32_e32 v199, v47, v123
	v_fmac_f32_e32 v200, v47, v124
	v_fmac_f32_e32 v201, v47, v125
	global_load_dwordx4 v[110:113], v84, s[10:11] offset:224
	global_load_dwordx4 v[114:117], v84, s[10:11] offset:240
	global_load_dwordx4 v[118:121], v84, s[12:13] offset:224
	global_load_dwordx4 v[122:125], v84, s[12:13] offset:240
	s_waitcnt vmcnt(4)
	v_fmac_f32_e32 v148, v16, v94
	v_fmac_f32_e32 v149, v16, v95
	v_fmac_f32_e32 v150, v16, v96
	v_fmac_f32_e32 v151, v16, v97
	v_fmac_f32_e32 v152, v16, v98
	v_fmac_f32_e32 v153, v16, v99
	v_fmac_f32_e32 v154, v16, v100
	v_fmac_f32_e32 v155, v16, v101
	v_fmac_f32_e32 v156, v16, v102
	v_fmac_f32_e32 v157, v16, v103
	v_fmac_f32_e32 v158, v16, v104
	v_fmac_f32_e32 v159, v16, v105
	v_fmac_f32_e32 v160, v16, v106
	v_fmac_f32_e32 v161, v16, v107
	v_fmac_f32_e32 v162, v16, v108
	v_fmac_f32_e32 v163, v16, v109
	v_fmac_f32_e32 v170, v32, v94
	v_fmac_f32_e32 v171, v32, v95
	v_fmac_f32_e32 v172, v32, v96
	v_fmac_f32_e32 v173, v32, v97
	v_fmac_f32_e32 v174, v32, v98
	v_fmac_f32_e32 v175, v32, v99
	v_fmac_f32_e32 v176, v32, v100
	v_fmac_f32_e32 v177, v32, v101
	v_fmac_f32_e32 v178, v32, v102
	v_fmac_f32_e32 v179, v32, v103
	v_fmac_f32_e32 v180, v32, v104
	v_fmac_f32_e32 v181, v32, v105
	v_fmac_f32_e32 v182, v32, v106
	v_fmac_f32_e32 v183, v32, v107
	v_fmac_f32_e32 v184, v32, v108
	v_fmac_f32_e32 v185, v32, v109
	v_fmac_f32_e32 v186, v48, v94
	v_fmac_f32_e32 v187, v48, v95
	v_fmac_f32_e32 v188, v48, v96
	v_fmac_f32_e32 v189, v48, v97
	v_fmac_f32_e32 v190, v48, v98
	v_fmac_f32_e32 v191, v48, v99
	v_fmac_f32_e32 v192, v48, v100
	v_fmac_f32_e32 v193, v48, v101
	v_fmac_f32_e32 v194, v48, v102
	v_fmac_f32_e32 v195, v48, v103
	v_fmac_f32_e32 v196, v48, v104
	v_fmac_f32_e32 v197, v48, v105
	v_fmac_f32_e32 v198, v48, v106
	v_fmac_f32_e32 v199, v48, v107
	v_fmac_f32_e32 v200, v48, v108
	v_fmac_f32_e32 v201, v48, v109
	s_waitcnt vmcnt(0)
	v_fmac_f32_e32 v148, v17, v110
	v_fmac_f32_e32 v149, v17, v111
	v_fmac_f32_e32 v150, v17, v112
	v_fmac_f32_e32 v151, v17, v113
	v_fmac_f32_e32 v152, v17, v114
	v_fmac_f32_e32 v153, v17, v115
	v_fmac_f32_e32 v154, v17, v116
	v_fmac_f32_e32 v155, v17, v117
	v_fmac_f32_e32 v156, v17, v118
	v_fmac_f32_e32 v157, v17, v119
	v_fmac_f32_e32 v158, v17, v120
	v_fmac_f32_e32 v159, v17, v121
	v_fmac_f32_e32 v160, v17, v122
	v_fmac_f32_e32 v161, v17, v123
	v_fmac_f32_e32 v162, v17, v124
	v_fmac_f32_e32 v163, v17, v125
	v_fmac_f32_e32 v170, v33, v110
	v_fmac_f32_e32 v171, v33, v111
	v_fmac_f32_e32 v172, v33, v112
	v_fmac_f32_e32 v173, v33, v113
	v_fmac_f32_e32 v174, v33, v114
	v_fmac_f32_e32 v175, v33, v115
	v_fmac_f32_e32 v176, v33, v116
	v_fmac_f32_e32 v177, v33, v117
	v_fmac_f32_e32 v178, v33, v118
	v_fmac_f32_e32 v179, v33, v119
	v_fmac_f32_e32 v180, v33, v120
	v_fmac_f32_e32 v181, v33, v121
	v_fmac_f32_e32 v182, v33, v122
	v_fmac_f32_e32 v183, v33, v123
	v_fmac_f32_e32 v184, v33, v124
	v_fmac_f32_e32 v185, v33, v125
	v_fmac_f32_e32 v186, v49, v110
	v_fmac_f32_e32 v187, v49, v111
	v_fmac_f32_e32 v188, v49, v112
	v_fmac_f32_e32 v189, v49, v113
	v_fmac_f32_e32 v190, v49, v114
	v_fmac_f32_e32 v191, v49, v115
	v_fmac_f32_e32 v192, v49, v116
	v_fmac_f32_e32 v193, v49, v117
	v_fmac_f32_e32 v194, v49, v118
	v_fmac_f32_e32 v195, v49, v119
	v_fmac_f32_e32 v196, v49, v120
	v_fmac_f32_e32 v197, v49, v121
	v_fmac_f32_e32 v198, v49, v122
	v_fmac_f32_e32 v199, v49, v123
	v_fmac_f32_e32 v200, v49, v124
	v_fmac_f32_e32 v201, v49, v125
	s_nop 1
	v_permlane32_swap_b32_e32 v148, v156
	v_permlane32_swap_b32_e32 v149, v157
	v_permlane32_swap_b32_e32 v150, v158
	v_permlane32_swap_b32_e32 v151, v159
	v_permlane32_swap_b32_e32 v152, v160
	v_permlane32_swap_b32_e32 v153, v161
	v_permlane32_swap_b32_e32 v154, v162
	v_permlane32_swap_b32_e32 v155, v163
	v_permlane32_swap_b32_e32 v170, v178
	v_permlane32_swap_b32_e32 v171, v179
	v_permlane32_swap_b32_e32 v172, v180
	v_permlane32_swap_b32_e32 v173, v181
	v_permlane32_swap_b32_e32 v174, v182
	v_permlane32_swap_b32_e32 v175, v183
	v_permlane32_swap_b32_e32 v176, v184
	v_permlane32_swap_b32_e32 v177, v185
	v_permlane32_swap_b32_e32 v186, v194
	v_permlane32_swap_b32_e32 v187, v195
	v_permlane32_swap_b32_e32 v188, v196
	v_permlane32_swap_b32_e32 v189, v197
	v_permlane32_swap_b32_e32 v190, v198
	v_permlane32_swap_b32_e32 v191, v199
	v_permlane32_swap_b32_e32 v192, v200
	v_permlane32_swap_b32_e32 v193, v201
	v_add_f32_e32 v148, v148, v156
	v_add_f32_e32 v149, v149, v157
	v_add_f32_e32 v150, v150, v158
	v_add_f32_e32 v151, v151, v159
	v_add_f32_e32 v152, v152, v160
	v_add_f32_e32 v153, v153, v161
	v_add_f32_e32 v154, v154, v162
	v_add_f32_e32 v155, v155, v163
	v_add_f32_e32 v170, v170, v178
	v_add_f32_e32 v171, v171, v179
	v_add_f32_e32 v172, v172, v180
	v_add_f32_e32 v173, v173, v181
	v_add_f32_e32 v174, v174, v182
	v_add_f32_e32 v175, v175, v183
	v_add_f32_e32 v176, v176, v184
	v_add_f32_e32 v177, v177, v185
	v_add_f32_e32 v186, v186, v194
	v_add_f32_e32 v187, v187, v195
	v_add_f32_e32 v188, v188, v196
	v_add_f32_e32 v189, v189, v197
	v_add_f32_e32 v190, v190, v198
	v_add_f32_e32 v191, v191, v199
	v_add_f32_e32 v192, v192, v200
	v_add_f32_e32 v193, v193, v201
	s_nop 1
	v_permlane16_swap_b32_e32 v148, v152
	v_permlane16_swap_b32_e32 v149, v153
	v_permlane16_swap_b32_e32 v150, v154
	v_permlane16_swap_b32_e32 v151, v155
	v_permlane16_swap_b32_e32 v170, v174
	v_permlane16_swap_b32_e32 v171, v175
	v_permlane16_swap_b32_e32 v172, v176
	v_permlane16_swap_b32_e32 v173, v177
	v_permlane16_swap_b32_e32 v186, v190
	v_permlane16_swap_b32_e32 v187, v191
	v_permlane16_swap_b32_e32 v188, v192
	v_permlane16_swap_b32_e32 v189, v193
	v_add_f32_e32 v148, v148, v152
	v_add_f32_e32 v149, v149, v153
	v_add_f32_e32 v150, v150, v154
	v_add_f32_e32 v151, v151, v155
	v_add_f32_e32 v170, v170, v174
	v_add_f32_e32 v171, v171, v175
	v_add_f32_e32 v172, v172, v176
	v_add_f32_e32 v173, v173, v177
	v_add_f32_e32 v186, v186, v190
	v_add_f32_e32 v187, v187, v191
	v_add_f32_e32 v188, v188, v192
	v_add_f32_e32 v189, v189, v193
	s_nop 1
	v_add_f32_dpp v148, v148, v148 row_ror:8 row_mask:0xf bank_mask:0xf
	v_add_f32_dpp v149, v149, v149 row_ror:8 row_mask:0xf bank_mask:0xf
	v_add_f32_dpp v150, v150, v150 row_ror:8 row_mask:0xf bank_mask:0xf
	v_add_f32_dpp v151, v151, v151 row_ror:8 row_mask:0xf bank_mask:0xf
	v_add_f32_dpp v170, v170, v170 row_ror:8 row_mask:0xf bank_mask:0xf
	v_add_f32_dpp v171, v171, v171 row_ror:8 row_mask:0xf bank_mask:0xf
	v_add_f32_dpp v172, v172, v172 row_ror:8 row_mask:0xf bank_mask:0xf
	v_add_f32_dpp v173, v173, v173 row_ror:8 row_mask:0xf bank_mask:0xf
	v_add_f32_dpp v186, v186, v186 row_ror:8 row_mask:0xf bank_mask:0xf
	v_add_f32_dpp v187, v187, v187 row_ror:8 row_mask:0xf bank_mask:0xf
	v_add_f32_dpp v188, v188, v188 row_ror:8 row_mask:0xf bank_mask:0xf
	v_add_f32_dpp v189, v189, v189 row_ror:8 row_mask:0xf bank_mask:0xf
	v_add_f32_dpp v148, v148, v148 row_ror:4 row_mask:0xf bank_mask:0xf
	v_add_f32_dpp v149, v149, v149 row_ror:4 row_mask:0xf bank_mask:0xf
	v_add_f32_dpp v150, v150, v150 row_ror:4 row_mask:0xf bank_mask:0xf
	v_add_f32_dpp v151, v151, v151 row_ror:4 row_mask:0xf bank_mask:0xf
	v_add_f32_dpp v170, v170, v170 row_ror:4 row_mask:0xf bank_mask:0xf
	v_add_f32_dpp v171, v171, v171 row_ror:4 row_mask:0xf bank_mask:0xf
	v_add_f32_dpp v172, v172, v172 row_ror:4 row_mask:0xf bank_mask:0xf
	v_add_f32_dpp v173, v173, v173 row_ror:4 row_mask:0xf bank_mask:0xf
	v_add_f32_dpp v186, v186, v186 row_ror:4 row_mask:0xf bank_mask:0xf
	v_add_f32_dpp v187, v187, v187 row_ror:4 row_mask:0xf bank_mask:0xf
	v_add_f32_dpp v188, v188, v188 row_ror:4 row_mask:0xf bank_mask:0xf
	v_add_f32_dpp v189, v189, v189 row_ror:4 row_mask:0xf bank_mask:0xf
	v_add_f32_dpp v148, v148, v148 row_ror:2 row_mask:0xf bank_mask:0xf
	v_add_f32_dpp v149, v149, v149 row_ror:2 row_mask:0xf bank_mask:0xf
	v_add_f32_dpp v150, v150, v150 row_ror:2 row_mask:0xf bank_mask:0xf
	v_add_f32_dpp v151, v151, v151 row_ror:2 row_mask:0xf bank_mask:0xf
	v_add_f32_dpp v170, v170, v170 row_ror:2 row_mask:0xf bank_mask:0xf
	v_add_f32_dpp v171, v171, v171 row_ror:2 row_mask:0xf bank_mask:0xf
	v_add_f32_dpp v172, v172, v172 row_ror:2 row_mask:0xf bank_mask:0xf
	v_add_f32_dpp v173, v173, v173 row_ror:2 row_mask:0xf bank_mask:0xf
	v_add_f32_dpp v186, v186, v186 row_ror:2 row_mask:0xf bank_mask:0xf
	v_add_f32_dpp v187, v187, v187 row_ror:2 row_mask:0xf bank_mask:0xf
	v_add_f32_dpp v188, v188, v188 row_ror:2 row_mask:0xf bank_mask:0xf
	v_add_f32_dpp v189, v189, v189 row_ror:2 row_mask:0xf bank_mask:0xf
	v_add_f32_dpp v148, v148, v148 row_ror:1 row_mask:0xf bank_mask:0xf
	v_add_f32_dpp v149, v149, v149 row_ror:1 row_mask:0xf bank_mask:0xf
	v_add_f32_dpp v150, v150, v150 row_ror:1 row_mask:0xf bank_mask:0xf
	v_add_f32_dpp v151, v151, v151 row_ror:1 row_mask:0xf bank_mask:0xf
	v_add_f32_dpp v170, v170, v170 row_ror:1 row_mask:0xf bank_mask:0xf
	v_add_f32_dpp v171, v171, v171 row_ror:1 row_mask:0xf bank_mask:0xf
	v_add_f32_dpp v172, v172, v172 row_ror:1 row_mask:0xf bank_mask:0xf
	v_add_f32_dpp v173, v173, v173 row_ror:1 row_mask:0xf bank_mask:0xf
	v_add_f32_dpp v186, v186, v186 row_ror:1 row_mask:0xf bank_mask:0xf
	v_add_f32_dpp v187, v187, v187 row_ror:1 row_mask:0xf bank_mask:0xf
	v_add_f32_dpp v188, v188, v188 row_ror:1 row_mask:0xf bank_mask:0xf
	v_add_f32_dpp v189, v189, v189 row_ror:1 row_mask:0xf bank_mask:0xf
	v_cndmask_b32_e64 v218, v148, v149, s[16:17]
	v_cndmask_b32_e64 v218, v218, v150, s[18:19]
	v_cndmask_b32_e64 v218, v218, v151, s[22:23]
	v_add_f32_e32 v218, v218, v216
	v_cndmask_b32_e64 v219, v170, v171, s[16:17]
	v_cndmask_b32_e64 v219, v219, v172, s[18:19]
	v_cndmask_b32_e64 v219, v219, v173, s[22:23]
	v_add_f32_e32 v219, v219, v216
	v_cndmask_b32_e64 v220, v186, v187, s[16:17]
	v_cndmask_b32_e64 v220, v220, v188, s[18:19]
	v_cndmask_b32_e64 v220, v220, v189, s[22:23]
	v_add_f32_e32 v220, v220, v216
	v_mul_f32_e64 v221, |v218|, s14
	v_mul_f32_e64 v222, |v219|, s14
	v_mul_f32_e64 v223, |v220|, s14
	v_exp_f32_e32 v221, v221
	v_exp_f32_e32 v222, v222
	v_exp_f32_e32 v223, v223
	s_nop 0
	v_add_f32_e32 v221, 1.0, v221
	v_add_f32_e32 v222, 1.0, v222
	v_add_f32_e32 v223, 1.0, v223
	v_log_f32_e32 v221, v221
	v_log_f32_e32 v222, v222
	v_log_f32_e32 v223, v223
	s_nop 0
	v_mul_f32_e32 v221, s28, v221
	v_mul_f32_e32 v222, s28, v222
	v_mul_f32_e32 v223, s28, v223
	v_min_f32_e32 v126, 0, v218
	v_min_f32_e32 v127, 0, v219
	v_min_f32_e32 v128, 0, v220
	v_sub_f32_e32 v126, v126, v221
	v_sub_f32_e32 v127, v127, v222
	v_sub_f32_e32 v128, v128, v223
	v_cndmask_b32_e64 v218, v218, v126, s[48:49]
	v_cndmask_b32_e64 v219, v219, v127, s[48:49]
	v_cndmask_b32_e64 v220, v220, v128, s[48:49]
	s_mov_b64 s[24:25], exec
	s_mov_b64 exec, s[26:27]
	global_store_dword v217, v218, s[20:21] offset:0
	global_store_dword v217, v219, s[20:21] offset:64
	global_store_dword v217, v220, s[20:21] offset:128
	s_mov_b64 exec, s[24:25]
	s_add_u32 s20, s20, 0xc0
	s_addc_u32 s21, s21, 0
	v_mov_b32_e32 v148, 0
	v_mov_b32_e32 v149, 0
	v_mov_b32_e32 v150, 0
	v_mov_b32_e32 v151, 0
	v_mov_b32_e32 v152, 0
	v_mov_b32_e32 v153, 0
	v_mov_b32_e32 v154, 0
	v_mov_b32_e32 v155, 0
	v_mov_b32_e32 v156, 0
	v_mov_b32_e32 v157, 0
	v_mov_b32_e32 v158, 0
	v_mov_b32_e32 v159, 0
	v_mov_b32_e32 v160, 0
	v_mov_b32_e32 v161, 0
	v_mov_b32_e32 v162, 0
	v_mov_b32_e32 v163, 0
	v_mov_b32_e32 v170, 0
	v_mov_b32_e32 v171, 0
	v_mov_b32_e32 v172, 0
	v_mov_b32_e32 v173, 0
	v_mov_b32_e32 v174, 0
	v_mov_b32_e32 v175, 0
	v_mov_b32_e32 v176, 0
	v_mov_b32_e32 v177, 0
	v_mov_b32_e32 v178, 0
	v_mov_b32_e32 v179, 0
	v_mov_b32_e32 v180, 0
	v_mov_b32_e32 v181, 0
	v_mov_b32_e32 v182, 0
	v_mov_b32_e32 v183, 0
	v_mov_b32_e32 v184, 0
	v_mov_b32_e32 v185, 0
	v_mov_b32_e32 v186, 0
	v_mov_b32_e32 v187, 0
	v_mov_b32_e32 v188, 0
	v_mov_b32_e32 v189, 0
	v_mov_b32_e32 v190, 0
	v_mov_b32_e32 v191, 0
	v_mov_b32_e32 v192, 0
	v_mov_b32_e32 v193, 0
	v_mov_b32_e32 v194, 0
	v_mov_b32_e32 v195, 0
	v_mov_b32_e32 v196, 0
	v_mov_b32_e32 v197, 0
	v_mov_b32_e32 v198, 0
	v_mov_b32_e32 v199, 0
	v_mov_b32_e32 v200, 0
	v_mov_b32_e32 v201, 0
	global_load_dwordx4 v[94:97], v84, s[6:7] offset:0
	global_load_dwordx4 v[98:101], v84, s[6:7] offset:16
	global_load_dwordx4 v[102:105], v84, s[8:9] offset:0
	global_load_dwordx4 v[106:109], v84, s[8:9] offset:16
	global_load_dwordx4 v[110:113], v84, s[6:7] offset:32
	global_load_dwordx4 v[114:117], v84, s[6:7] offset:48
	global_load_dwordx4 v[118:121], v84, s[8:9] offset:32
	global_load_dwordx4 v[122:125], v84, s[8:9] offset:48
	s_waitcnt vmcnt(4)
	v_fmac_f32_e32 v148, v50, v94
	v_fmac_f32_e32 v149, v50, v95
	v_fmac_f32_e32 v150, v50, v96
	v_fmac_f32_e32 v151, v50, v97
	v_fmac_f32_e32 v152, v50, v98
	v_fmac_f32_e32 v153, v50, v99
	v_fmac_f32_e32 v154, v50, v100
	v_fmac_f32_e32 v155, v50, v101
	v_fmac_f32_e32 v156, v50, v102
	v_fmac_f32_e32 v157, v50, v103
	v_fmac_f32_e32 v158, v50, v104
	v_fmac_f32_e32 v159, v50, v105
	v_fmac_f32_e32 v160, v50, v106
	v_fmac_f32_e32 v161, v50, v107
	v_fmac_f32_e32 v162, v50, v108
	v_fmac_f32_e32 v163, v50, v109
	v_fmac_f32_e32 v170, v66, v94
	v_fmac_f32_e32 v171, v66, v95
	v_fmac_f32_e32 v172, v66, v96
	v_fmac_f32_e32 v173, v66, v97
	v_fmac_f32_e32 v174, v66, v98
	v_fmac_f32_e32 v175, v66, v99
	v_fmac_f32_e32 v176, v66, v100
	v_fmac_f32_e32 v177, v66, v101
	v_fmac_f32_e32 v178, v66, v102
	v_fmac_f32_e32 v179, v66, v103
	v_fmac_f32_e32 v180, v66, v104
	v_fmac_f32_e32 v181, v66, v105
	v_fmac_f32_e32 v182, v66, v106
	v_fmac_f32_e32 v183, v66, v107
	v_fmac_f32_e32 v184, v66, v108
	v_fmac_f32_e32 v185, v66, v109
	v_fmac_f32_e32 v186, v132, v94
	v_fmac_f32_e32 v187, v132, v95
	v_fmac_f32_e32 v188, v132, v96
	v_fmac_f32_e32 v189, v132, v97
	v_fmac_f32_e32 v190, v132, v98
	v_fmac_f32_e32 v191, v132, v99
	v_fmac_f32_e32 v192, v132, v100
	v_fmac_f32_e32 v193, v132, v101
	v_fmac_f32_e32 v194, v132, v102
	v_fmac_f32_e32 v195, v132, v103
	v_fmac_f32_e32 v196, v132, v104
	v_fmac_f32_e32 v197, v132, v105
	v_fmac_f32_e32 v198, v132, v106
	v_fmac_f32_e32 v199, v132, v107
	v_fmac_f32_e32 v200, v132, v108
	v_fmac_f32_e32 v201, v132, v109
	global_load_dwordx4 v[94:97], v84, s[6:7] offset:64
	global_load_dwordx4 v[98:101], v84, s[6:7] offset:80
	global_load_dwordx4 v[102:105], v84, s[8:9] offset:64
	global_load_dwordx4 v[106:109], v84, s[8:9] offset:80
	s_waitcnt vmcnt(4)
	v_fmac_f32_e32 v148, v51, v110
	v_fmac_f32_e32 v149, v51, v111
	v_fmac_f32_e32 v150, v51, v112
	v_fmac_f32_e32 v151, v51, v113
	v_fmac_f32_e32 v152, v51, v114
	v_fmac_f32_e32 v153, v51, v115
	v_fmac_f32_e32 v154, v51, v116
	v_fmac_f32_e32 v155, v51, v117
	v_fmac_f32_e32 v156, v51, v118
	v_fmac_f32_e32 v157, v51, v119
	v_fmac_f32_e32 v158, v51, v120
	v_fmac_f32_e32 v159, v51, v121
	v_fmac_f32_e32 v160, v51, v122
	v_fmac_f32_e32 v161, v51, v123
	v_fmac_f32_e32 v162, v51, v124
	v_fmac_f32_e32 v163, v51, v125
	v_fmac_f32_e32 v170, v67, v110
	v_fmac_f32_e32 v171, v67, v111
	v_fmac_f32_e32 v172, v67, v112
	v_fmac_f32_e32 v173, v67, v113
	v_fmac_f32_e32 v174, v67, v114
	v_fmac_f32_e32 v175, v67, v115
	v_fmac_f32_e32 v176, v67, v116
	v_fmac_f32_e32 v177, v67, v117
	v_fmac_f32_e32 v178, v67, v118
	v_fmac_f32_e32 v179, v67, v119
	v_fmac_f32_e32 v180, v67, v120
	v_fmac_f32_e32 v181, v67, v121
	v_fmac_f32_e32 v182, v67, v122
	v_fmac_f32_e32 v183, v67, v123
	v_fmac_f32_e32 v184, v67, v124
	v_fmac_f32_e32 v185, v67, v125
	v_fmac_f32_e32 v186, v133, v110
	v_fmac_f32_e32 v187, v133, v111
	v_fmac_f32_e32 v188, v133, v112
	v_fmac_f32_e32 v189, v133, v113
	v_fmac_f32_e32 v190, v133, v114
	v_fmac_f32_e32 v191, v133, v115
	v_fmac_f32_e32 v192, v133, v116
	v_fmac_f32_e32 v193, v133, v117
	v_fmac_f32_e32 v194, v133, v118
	v_fmac_f32_e32 v195, v133, v119
	v_fmac_f32_e32 v196, v133, v120
	v_fmac_f32_e32 v197, v133, v121
	v_fmac_f32_e32 v198, v133, v122
	v_fmac_f32_e32 v199, v133, v123
	v_fmac_f32_e32 v200, v133, v124
	v_fmac_f32_e32 v201, v133, v125
	global_load_dwordx4 v[110:113], v84, s[6:7] offset:96
	global_load_dwordx4 v[114:117], v84, s[6:7] offset:112
	global_load_dwordx4 v[118:121], v84, s[8:9] offset:96
	global_load_dwordx4 v[122:125], v84, s[8:9] offset:112
	s_waitcnt vmcnt(4)
	v_fmac_f32_e32 v148, v52, v94
	v_fmac_f32_e32 v149, v52, v95
	v_fmac_f32_e32 v150, v52, v96
	v_fmac_f32_e32 v151, v52, v97
	v_fmac_f32_e32 v152, v52, v98
	v_fmac_f32_e32 v153, v52, v99
	v_fmac_f32_e32 v154, v52, v100
	v_fmac_f32_e32 v155, v52, v101
	v_fmac_f32_e32 v156, v52, v102
	v_fmac_f32_e32 v157, v52, v103
	v_fmac_f32_e32 v158, v52, v104
	v_fmac_f32_e32 v159, v52, v105
	v_fmac_f32_e32 v160, v52, v106
	v_fmac_f32_e32 v161, v52, v107
	v_fmac_f32_e32 v162, v52, v108
	v_fmac_f32_e32 v163, v52, v109
	v_fmac_f32_e32 v170, v68, v94
	v_fmac_f32_e32 v171, v68, v95
	v_fmac_f32_e32 v172, v68, v96
	v_fmac_f32_e32 v173, v68, v97
	v_fmac_f32_e32 v174, v68, v98
	v_fmac_f32_e32 v175, v68, v99
	v_fmac_f32_e32 v176, v68, v100
	v_fmac_f32_e32 v177, v68, v101
	v_fmac_f32_e32 v178, v68, v102
	v_fmac_f32_e32 v179, v68, v103
	v_fmac_f32_e32 v180, v68, v104
	v_fmac_f32_e32 v181, v68, v105
	v_fmac_f32_e32 v182, v68, v106
	v_fmac_f32_e32 v183, v68, v107
	v_fmac_f32_e32 v184, v68, v108
	v_fmac_f32_e32 v185, v68, v109
	v_fmac_f32_e32 v186, v134, v94
	v_fmac_f32_e32 v187, v134, v95
	v_fmac_f32_e32 v188, v134, v96
	v_fmac_f32_e32 v189, v134, v97
	v_fmac_f32_e32 v190, v134, v98
	v_fmac_f32_e32 v191, v134, v99
	v_fmac_f32_e32 v192, v134, v100
	v_fmac_f32_e32 v193, v134, v101
	v_fmac_f32_e32 v194, v134, v102
	v_fmac_f32_e32 v195, v134, v103
	v_fmac_f32_e32 v196, v134, v104
	v_fmac_f32_e32 v197, v134, v105
	v_fmac_f32_e32 v198, v134, v106
	v_fmac_f32_e32 v199, v134, v107
	v_fmac_f32_e32 v200, v134, v108
	v_fmac_f32_e32 v201, v134, v109
	global_load_dwordx4 v[94:97], v84, s[6:7] offset:128
	global_load_dwordx4 v[98:101], v84, s[6:7] offset:144
	global_load_dwordx4 v[102:105], v84, s[8:9] offset:128
	global_load_dwordx4 v[106:109], v84, s[8:9] offset:144
	s_waitcnt vmcnt(4)
	v_fmac_f32_e32 v148, v53, v110
	v_fmac_f32_e32 v149, v53, v111
	v_fmac_f32_e32 v150, v53, v112
	v_fmac_f32_e32 v151, v53, v113
	v_fmac_f32_e32 v152, v53, v114
	v_fmac_f32_e32 v153, v53, v115
	v_fmac_f32_e32 v154, v53, v116
	v_fmac_f32_e32 v155, v53, v117
	v_fmac_f32_e32 v156, v53, v118
	v_fmac_f32_e32 v157, v53, v119
	v_fmac_f32_e32 v158, v53, v120
	v_fmac_f32_e32 v159, v53, v121
	v_fmac_f32_e32 v160, v53, v122
	v_fmac_f32_e32 v161, v53, v123
	v_fmac_f32_e32 v162, v53, v124
	v_fmac_f32_e32 v163, v53, v125
	v_fmac_f32_e32 v170, v69, v110
	v_fmac_f32_e32 v171, v69, v111
	v_fmac_f32_e32 v172, v69, v112
	v_fmac_f32_e32 v173, v69, v113
	v_fmac_f32_e32 v174, v69, v114
	v_fmac_f32_e32 v175, v69, v115
	v_fmac_f32_e32 v176, v69, v116
	v_fmac_f32_e32 v177, v69, v117
	v_fmac_f32_e32 v178, v69, v118
	v_fmac_f32_e32 v179, v69, v119
	v_fmac_f32_e32 v180, v69, v120
	v_fmac_f32_e32 v181, v69, v121
	v_fmac_f32_e32 v182, v69, v122
	v_fmac_f32_e32 v183, v69, v123
	v_fmac_f32_e32 v184, v69, v124
	v_fmac_f32_e32 v185, v69, v125
	v_fmac_f32_e32 v186, v135, v110
	v_fmac_f32_e32 v187, v135, v111
	v_fmac_f32_e32 v188, v135, v112
	v_fmac_f32_e32 v189, v135, v113
	v_fmac_f32_e32 v190, v135, v114
	v_fmac_f32_e32 v191, v135, v115
	v_fmac_f32_e32 v192, v135, v116
	v_fmac_f32_e32 v193, v135, v117
	v_fmac_f32_e32 v194, v135, v118
	v_fmac_f32_e32 v195, v135, v119
	v_fmac_f32_e32 v196, v135, v120
	v_fmac_f32_e32 v197, v135, v121
	v_fmac_f32_e32 v198, v135, v122
	v_fmac_f32_e32 v199, v135, v123
	v_fmac_f32_e32 v200, v135, v124
	v_fmac_f32_e32 v201, v135, v125
	global_load_dwordx4 v[110:113], v84, s[6:7] offset:160
	global_load_dwordx4 v[114:117], v84, s[6:7] offset:176
	global_load_dwordx4 v[118:121], v84, s[8:9] offset:160
	global_load_dwordx4 v[122:125], v84, s[8:9] offset:176
	s_waitcnt vmcnt(4)
	v_fmac_f32_e32 v148, v54, v94
	v_fmac_f32_e32 v149, v54, v95
	v_fmac_f32_e32 v150, v54, v96
	v_fmac_f32_e32 v151, v54, v97
	v_fmac_f32_e32 v152, v54, v98
	v_fmac_f32_e32 v153, v54, v99
	v_fmac_f32_e32 v154, v54, v100
	v_fmac_f32_e32 v155, v54, v101
	v_fmac_f32_e32 v156, v54, v102
	v_fmac_f32_e32 v157, v54, v103
	v_fmac_f32_e32 v158, v54, v104
	v_fmac_f32_e32 v159, v54, v105
	v_fmac_f32_e32 v160, v54, v106
	v_fmac_f32_e32 v161, v54, v107
	v_fmac_f32_e32 v162, v54, v108
	v_fmac_f32_e32 v163, v54, v109
	v_fmac_f32_e32 v170, v70, v94
	v_fmac_f32_e32 v171, v70, v95
	v_fmac_f32_e32 v172, v70, v96
	v_fmac_f32_e32 v173, v70, v97
	v_fmac_f32_e32 v174, v70, v98
	v_fmac_f32_e32 v175, v70, v99
	v_fmac_f32_e32 v176, v70, v100
	v_fmac_f32_e32 v177, v70, v101
	v_fmac_f32_e32 v178, v70, v102
	v_fmac_f32_e32 v179, v70, v103
	v_fmac_f32_e32 v180, v70, v104
	v_fmac_f32_e32 v181, v70, v105
	v_fmac_f32_e32 v182, v70, v106
	v_fmac_f32_e32 v183, v70, v107
	v_fmac_f32_e32 v184, v70, v108
	v_fmac_f32_e32 v185, v70, v109
	v_fmac_f32_e32 v186, v136, v94
	v_fmac_f32_e32 v187, v136, v95
	v_fmac_f32_e32 v188, v136, v96
	v_fmac_f32_e32 v189, v136, v97
	v_fmac_f32_e32 v190, v136, v98
	v_fmac_f32_e32 v191, v136, v99
	v_fmac_f32_e32 v192, v136, v100
	v_fmac_f32_e32 v193, v136, v101
	v_fmac_f32_e32 v194, v136, v102
	v_fmac_f32_e32 v195, v136, v103
	v_fmac_f32_e32 v196, v136, v104
	v_fmac_f32_e32 v197, v136, v105
	v_fmac_f32_e32 v198, v136, v106
	v_fmac_f32_e32 v199, v136, v107
	v_fmac_f32_e32 v200, v136, v108
	v_fmac_f32_e32 v201, v136, v109
	global_load_dwordx4 v[94:97], v84, s[6:7] offset:192
	global_load_dwordx4 v[98:101], v84, s[6:7] offset:208
	global_load_dwordx4 v[102:105], v84, s[8:9] offset:192
	global_load_dwordx4 v[106:109], v84, s[8:9] offset:208
	s_waitcnt vmcnt(4)
	v_fmac_f32_e32 v148, v55, v110
	v_fmac_f32_e32 v149, v55, v111
	v_fmac_f32_e32 v150, v55, v112
	v_fmac_f32_e32 v151, v55, v113
	v_fmac_f32_e32 v152, v55, v114
	v_fmac_f32_e32 v153, v55, v115
	v_fmac_f32_e32 v154, v55, v116
	v_fmac_f32_e32 v155, v55, v117
	v_fmac_f32_e32 v156, v55, v118
	v_fmac_f32_e32 v157, v55, v119
	v_fmac_f32_e32 v158, v55, v120
	v_fmac_f32_e32 v159, v55, v121
	v_fmac_f32_e32 v160, v55, v122
	v_fmac_f32_e32 v161, v55, v123
	v_fmac_f32_e32 v162, v55, v124
	v_fmac_f32_e32 v163, v55, v125
	v_fmac_f32_e32 v170, v71, v110
	v_fmac_f32_e32 v171, v71, v111
	v_fmac_f32_e32 v172, v71, v112
	v_fmac_f32_e32 v173, v71, v113
	v_fmac_f32_e32 v174, v71, v114
	v_fmac_f32_e32 v175, v71, v115
	v_fmac_f32_e32 v176, v71, v116
	v_fmac_f32_e32 v177, v71, v117
	v_fmac_f32_e32 v178, v71, v118
	v_fmac_f32_e32 v179, v71, v119
	v_fmac_f32_e32 v180, v71, v120
	v_fmac_f32_e32 v181, v71, v121
	v_fmac_f32_e32 v182, v71, v122
	v_fmac_f32_e32 v183, v71, v123
	v_fmac_f32_e32 v184, v71, v124
	v_fmac_f32_e32 v185, v71, v125
	v_fmac_f32_e32 v186, v137, v110
	v_fmac_f32_e32 v187, v137, v111
	v_fmac_f32_e32 v188, v137, v112
	v_fmac_f32_e32 v189, v137, v113
	v_fmac_f32_e32 v190, v137, v114
	v_fmac_f32_e32 v191, v137, v115
	v_fmac_f32_e32 v192, v137, v116
	v_fmac_f32_e32 v193, v137, v117
	v_fmac_f32_e32 v194, v137, v118
	v_fmac_f32_e32 v195, v137, v119
	v_fmac_f32_e32 v196, v137, v120
	v_fmac_f32_e32 v197, v137, v121
	v_fmac_f32_e32 v198, v137, v122
	v_fmac_f32_e32 v199, v137, v123
	v_fmac_f32_e32 v200, v137, v124
	v_fmac_f32_e32 v201, v137, v125
	global_load_dwordx4 v[110:113], v84, s[6:7] offset:224
	global_load_dwordx4 v[114:117], v84, s[6:7] offset:240
	global_load_dwordx4 v[118:121], v84, s[8:9] offset:224
	global_load_dwordx4 v[122:125], v84, s[8:9] offset:240
	s_waitcnt vmcnt(4)
	v_fmac_f32_e32 v148, v56, v94
	v_fmac_f32_e32 v149, v56, v95
	v_fmac_f32_e32 v150, v56, v96
	v_fmac_f32_e32 v151, v56, v97
	v_fmac_f32_e32 v152, v56, v98
	v_fmac_f32_e32 v153, v56, v99
	v_fmac_f32_e32 v154, v56, v100
	v_fmac_f32_e32 v155, v56, v101
	v_fmac_f32_e32 v156, v56, v102
	v_fmac_f32_e32 v157, v56, v103
	v_fmac_f32_e32 v158, v56, v104
	v_fmac_f32_e32 v159, v56, v105
	v_fmac_f32_e32 v160, v56, v106
	v_fmac_f32_e32 v161, v56, v107
	v_fmac_f32_e32 v162, v56, v108
	v_fmac_f32_e32 v163, v56, v109
	v_fmac_f32_e32 v170, v72, v94
	v_fmac_f32_e32 v171, v72, v95
	v_fmac_f32_e32 v172, v72, v96
	v_fmac_f32_e32 v173, v72, v97
	v_fmac_f32_e32 v174, v72, v98
	v_fmac_f32_e32 v175, v72, v99
	v_fmac_f32_e32 v176, v72, v100
	v_fmac_f32_e32 v177, v72, v101
	v_fmac_f32_e32 v178, v72, v102
	v_fmac_f32_e32 v179, v72, v103
	v_fmac_f32_e32 v180, v72, v104
	v_fmac_f32_e32 v181, v72, v105
	v_fmac_f32_e32 v182, v72, v106
	v_fmac_f32_e32 v183, v72, v107
	v_fmac_f32_e32 v184, v72, v108
	v_fmac_f32_e32 v185, v72, v109
	v_fmac_f32_e32 v186, v138, v94
	v_fmac_f32_e32 v187, v138, v95
	v_fmac_f32_e32 v188, v138, v96
	v_fmac_f32_e32 v189, v138, v97
	v_fmac_f32_e32 v190, v138, v98
	v_fmac_f32_e32 v191, v138, v99
	v_fmac_f32_e32 v192, v138, v100
	v_fmac_f32_e32 v193, v138, v101
	v_fmac_f32_e32 v194, v138, v102
	v_fmac_f32_e32 v195, v138, v103
	v_fmac_f32_e32 v196, v138, v104
	v_fmac_f32_e32 v197, v138, v105
	v_fmac_f32_e32 v198, v138, v106
	v_fmac_f32_e32 v199, v138, v107
	v_fmac_f32_e32 v200, v138, v108
	v_fmac_f32_e32 v201, v138, v109
	global_load_dwordx4 v[94:97], v84, s[10:11] offset:0
	global_load_dwordx4 v[98:101], v84, s[10:11] offset:16
	global_load_dwordx4 v[102:105], v84, s[12:13] offset:0
	global_load_dwordx4 v[106:109], v84, s[12:13] offset:16
	s_waitcnt vmcnt(4)
	v_fmac_f32_e32 v148, v57, v110
	v_fmac_f32_e32 v149, v57, v111
	v_fmac_f32_e32 v150, v57, v112
	v_fmac_f32_e32 v151, v57, v113
	v_fmac_f32_e32 v152, v57, v114
	v_fmac_f32_e32 v153, v57, v115
	v_fmac_f32_e32 v154, v57, v116
	v_fmac_f32_e32 v155, v57, v117
	v_fmac_f32_e32 v156, v57, v118
	v_fmac_f32_e32 v157, v57, v119
	v_fmac_f32_e32 v158, v57, v120
	v_fmac_f32_e32 v159, v57, v121
	v_fmac_f32_e32 v160, v57, v122
	v_fmac_f32_e32 v161, v57, v123
	v_fmac_f32_e32 v162, v57, v124
	v_fmac_f32_e32 v163, v57, v125
	v_fmac_f32_e32 v170, v73, v110
	v_fmac_f32_e32 v171, v73, v111
	v_fmac_f32_e32 v172, v73, v112
	v_fmac_f32_e32 v173, v73, v113
	v_fmac_f32_e32 v174, v73, v114
	v_fmac_f32_e32 v175, v73, v115
	v_fmac_f32_e32 v176, v73, v116
	v_fmac_f32_e32 v177, v73, v117
	v_fmac_f32_e32 v178, v73, v118
	v_fmac_f32_e32 v179, v73, v119
	v_fmac_f32_e32 v180, v73, v120
	v_fmac_f32_e32 v181, v73, v121
	v_fmac_f32_e32 v182, v73, v122
	v_fmac_f32_e32 v183, v73, v123
	v_fmac_f32_e32 v184, v73, v124
	v_fmac_f32_e32 v185, v73, v125
	v_fmac_f32_e32 v186, v139, v110
	v_fmac_f32_e32 v187, v139, v111
	v_fmac_f32_e32 v188, v139, v112
	v_fmac_f32_e32 v189, v139, v113
	v_fmac_f32_e32 v190, v139, v114
	v_fmac_f32_e32 v191, v139, v115
	v_fmac_f32_e32 v192, v139, v116
	v_fmac_f32_e32 v193, v139, v117
	v_fmac_f32_e32 v194, v139, v118
	v_fmac_f32_e32 v195, v139, v119
	v_fmac_f32_e32 v196, v139, v120
	v_fmac_f32_e32 v197, v139, v121
	v_fmac_f32_e32 v198, v139, v122
	v_fmac_f32_e32 v199, v139, v123
	v_fmac_f32_e32 v200, v139, v124
	v_fmac_f32_e32 v201, v139, v125
	global_load_dwordx4 v[110:113], v84, s[10:11] offset:32
	global_load_dwordx4 v[114:117], v84, s[10:11] offset:48
	global_load_dwordx4 v[118:121], v84, s[12:13] offset:32
	global_load_dwordx4 v[122:125], v84, s[12:13] offset:48
	s_waitcnt vmcnt(4)
	v_fmac_f32_e32 v148, v58, v94
	v_fmac_f32_e32 v149, v58, v95
	v_fmac_f32_e32 v150, v58, v96
	v_fmac_f32_e32 v151, v58, v97
	v_fmac_f32_e32 v152, v58, v98
	v_fmac_f32_e32 v153, v58, v99
	v_fmac_f32_e32 v154, v58, v100
	v_fmac_f32_e32 v155, v58, v101
	v_fmac_f32_e32 v156, v58, v102
	v_fmac_f32_e32 v157, v58, v103
	v_fmac_f32_e32 v158, v58, v104
	v_fmac_f32_e32 v159, v58, v105
	v_fmac_f32_e32 v160, v58, v106
	v_fmac_f32_e32 v161, v58, v107
	v_fmac_f32_e32 v162, v58, v108
	v_fmac_f32_e32 v163, v58, v109
	v_fmac_f32_e32 v170, v74, v94
	v_fmac_f32_e32 v171, v74, v95
	v_fmac_f32_e32 v172, v74, v96
	v_fmac_f32_e32 v173, v74, v97
	v_fmac_f32_e32 v174, v74, v98
	v_fmac_f32_e32 v175, v74, v99
	v_fmac_f32_e32 v176, v74, v100
	v_fmac_f32_e32 v177, v74, v101
	v_fmac_f32_e32 v178, v74, v102
	v_fmac_f32_e32 v179, v74, v103
	v_fmac_f32_e32 v180, v74, v104
	v_fmac_f32_e32 v181, v74, v105
	v_fmac_f32_e32 v182, v74, v106
	v_fmac_f32_e32 v183, v74, v107
	v_fmac_f32_e32 v184, v74, v108
	v_fmac_f32_e32 v185, v74, v109
	v_fmac_f32_e32 v186, v140, v94
	v_fmac_f32_e32 v187, v140, v95
	v_fmac_f32_e32 v188, v140, v96
	v_fmac_f32_e32 v189, v140, v97
	v_fmac_f32_e32 v190, v140, v98
	v_fmac_f32_e32 v191, v140, v99
	v_fmac_f32_e32 v192, v140, v100
	v_fmac_f32_e32 v193, v140, v101
	v_fmac_f32_e32 v194, v140, v102
	v_fmac_f32_e32 v195, v140, v103
	v_fmac_f32_e32 v196, v140, v104
	v_fmac_f32_e32 v197, v140, v105
	v_fmac_f32_e32 v198, v140, v106
	v_fmac_f32_e32 v199, v140, v107
	v_fmac_f32_e32 v200, v140, v108
	v_fmac_f32_e32 v201, v140, v109
	global_load_dwordx4 v[94:97], v84, s[10:11] offset:64
	global_load_dwordx4 v[98:101], v84, s[10:11] offset:80
	global_load_dwordx4 v[102:105], v84, s[12:13] offset:64
	global_load_dwordx4 v[106:109], v84, s[12:13] offset:80
	s_waitcnt vmcnt(4)
	v_fmac_f32_e32 v148, v59, v110
	v_fmac_f32_e32 v149, v59, v111
	v_fmac_f32_e32 v150, v59, v112
	v_fmac_f32_e32 v151, v59, v113
	v_fmac_f32_e32 v152, v59, v114
	v_fmac_f32_e32 v153, v59, v115
	v_fmac_f32_e32 v154, v59, v116
	v_fmac_f32_e32 v155, v59, v117
	v_fmac_f32_e32 v156, v59, v118
	v_fmac_f32_e32 v157, v59, v119
	v_fmac_f32_e32 v158, v59, v120
	v_fmac_f32_e32 v159, v59, v121
	v_fmac_f32_e32 v160, v59, v122
	v_fmac_f32_e32 v161, v59, v123
	v_fmac_f32_e32 v162, v59, v124
	v_fmac_f32_e32 v163, v59, v125
	v_fmac_f32_e32 v170, v75, v110
	v_fmac_f32_e32 v171, v75, v111
	v_fmac_f32_e32 v172, v75, v112
	v_fmac_f32_e32 v173, v75, v113
	v_fmac_f32_e32 v174, v75, v114
	v_fmac_f32_e32 v175, v75, v115
	v_fmac_f32_e32 v176, v75, v116
	v_fmac_f32_e32 v177, v75, v117
	v_fmac_f32_e32 v178, v75, v118
	v_fmac_f32_e32 v179, v75, v119
	v_fmac_f32_e32 v180, v75, v120
	v_fmac_f32_e32 v181, v75, v121
	v_fmac_f32_e32 v182, v75, v122
	v_fmac_f32_e32 v183, v75, v123
	v_fmac_f32_e32 v184, v75, v124
	v_fmac_f32_e32 v185, v75, v125
	v_fmac_f32_e32 v186, v141, v110
	v_fmac_f32_e32 v187, v141, v111
	v_fmac_f32_e32 v188, v141, v112
	v_fmac_f32_e32 v189, v141, v113
	v_fmac_f32_e32 v190, v141, v114
	v_fmac_f32_e32 v191, v141, v115
	v_fmac_f32_e32 v192, v141, v116
	v_fmac_f32_e32 v193, v141, v117
	v_fmac_f32_e32 v194, v141, v118
	v_fmac_f32_e32 v195, v141, v119
	v_fmac_f32_e32 v196, v141, v120
	v_fmac_f32_e32 v197, v141, v121
	v_fmac_f32_e32 v198, v141, v122
	v_fmac_f32_e32 v199, v141, v123
	v_fmac_f32_e32 v200, v141, v124
	v_fmac_f32_e32 v201, v141, v125
	global_load_dwordx4 v[110:113], v84, s[10:11] offset:96
	global_load_dwordx4 v[114:117], v84, s[10:11] offset:112
	global_load_dwordx4 v[118:121], v84, s[12:13] offset:96
	global_load_dwordx4 v[122:125], v84, s[12:13] offset:112
	s_waitcnt vmcnt(4)
	v_fmac_f32_e32 v148, v60, v94
	v_fmac_f32_e32 v149, v60, v95
	v_fmac_f32_e32 v150, v60, v96
	v_fmac_f32_e32 v151, v60, v97
	v_fmac_f32_e32 v152, v60, v98
	v_fmac_f32_e32 v153, v60, v99
	v_fmac_f32_e32 v154, v60, v100
	v_fmac_f32_e32 v155, v60, v101
	v_fmac_f32_e32 v156, v60, v102
	v_fmac_f32_e32 v157, v60, v103
	v_fmac_f32_e32 v158, v60, v104
	v_fmac_f32_e32 v159, v60, v105
	v_fmac_f32_e32 v160, v60, v106
	v_fmac_f32_e32 v161, v60, v107
	v_fmac_f32_e32 v162, v60, v108
	v_fmac_f32_e32 v163, v60, v109
	v_fmac_f32_e32 v170, v76, v94
	v_fmac_f32_e32 v171, v76, v95
	v_fmac_f32_e32 v172, v76, v96
	v_fmac_f32_e32 v173, v76, v97
	v_fmac_f32_e32 v174, v76, v98
	v_fmac_f32_e32 v175, v76, v99
	v_fmac_f32_e32 v176, v76, v100
	v_fmac_f32_e32 v177, v76, v101
	v_fmac_f32_e32 v178, v76, v102
	v_fmac_f32_e32 v179, v76, v103
	v_fmac_f32_e32 v180, v76, v104
	v_fmac_f32_e32 v181, v76, v105
	v_fmac_f32_e32 v182, v76, v106
	v_fmac_f32_e32 v183, v76, v107
	v_fmac_f32_e32 v184, v76, v108
	v_fmac_f32_e32 v185, v76, v109
	v_fmac_f32_e32 v186, v142, v94
	v_fmac_f32_e32 v187, v142, v95
	v_fmac_f32_e32 v188, v142, v96
	v_fmac_f32_e32 v189, v142, v97
	v_fmac_f32_e32 v190, v142, v98
	v_fmac_f32_e32 v191, v142, v99
	v_fmac_f32_e32 v192, v142, v100
	v_fmac_f32_e32 v193, v142, v101
	v_fmac_f32_e32 v194, v142, v102
	v_fmac_f32_e32 v195, v142, v103
	v_fmac_f32_e32 v196, v142, v104
	v_fmac_f32_e32 v197, v142, v105
	v_fmac_f32_e32 v198, v142, v106
	v_fmac_f32_e32 v199, v142, v107
	v_fmac_f32_e32 v200, v142, v108
	v_fmac_f32_e32 v201, v142, v109
	global_load_dwordx4 v[94:97], v84, s[10:11] offset:128
	global_load_dwordx4 v[98:101], v84, s[10:11] offset:144
	global_load_dwordx4 v[102:105], v84, s[12:13] offset:128
	global_load_dwordx4 v[106:109], v84, s[12:13] offset:144
	s_waitcnt vmcnt(4)
	v_fmac_f32_e32 v148, v61, v110
	v_fmac_f32_e32 v149, v61, v111
	v_fmac_f32_e32 v150, v61, v112
	v_fmac_f32_e32 v151, v61, v113
	v_fmac_f32_e32 v152, v61, v114
	v_fmac_f32_e32 v153, v61, v115
	v_fmac_f32_e32 v154, v61, v116
	v_fmac_f32_e32 v155, v61, v117
	v_fmac_f32_e32 v156, v61, v118
	v_fmac_f32_e32 v157, v61, v119
	v_fmac_f32_e32 v158, v61, v120
	v_fmac_f32_e32 v159, v61, v121
	v_fmac_f32_e32 v160, v61, v122
	v_fmac_f32_e32 v161, v61, v123
	v_fmac_f32_e32 v162, v61, v124
	v_fmac_f32_e32 v163, v61, v125
	v_fmac_f32_e32 v170, v77, v110
	v_fmac_f32_e32 v171, v77, v111
	v_fmac_f32_e32 v172, v77, v112
	v_fmac_f32_e32 v173, v77, v113
	v_fmac_f32_e32 v174, v77, v114
	v_fmac_f32_e32 v175, v77, v115
	v_fmac_f32_e32 v176, v77, v116
	v_fmac_f32_e32 v177, v77, v117
	v_fmac_f32_e32 v178, v77, v118
	v_fmac_f32_e32 v179, v77, v119
	v_fmac_f32_e32 v180, v77, v120
	v_fmac_f32_e32 v181, v77, v121
	v_fmac_f32_e32 v182, v77, v122
	v_fmac_f32_e32 v183, v77, v123
	v_fmac_f32_e32 v184, v77, v124
	v_fmac_f32_e32 v185, v77, v125
	v_fmac_f32_e32 v186, v143, v110
	v_fmac_f32_e32 v187, v143, v111
	v_fmac_f32_e32 v188, v143, v112
	v_fmac_f32_e32 v189, v143, v113
	v_fmac_f32_e32 v190, v143, v114
	v_fmac_f32_e32 v191, v143, v115
	v_fmac_f32_e32 v192, v143, v116
	v_fmac_f32_e32 v193, v143, v117
	v_fmac_f32_e32 v194, v143, v118
	v_fmac_f32_e32 v195, v143, v119
	v_fmac_f32_e32 v196, v143, v120
	v_fmac_f32_e32 v197, v143, v121
	v_fmac_f32_e32 v198, v143, v122
	v_fmac_f32_e32 v199, v143, v123
	v_fmac_f32_e32 v200, v143, v124
	v_fmac_f32_e32 v201, v143, v125
	global_load_dwordx4 v[110:113], v84, s[10:11] offset:160
	global_load_dwordx4 v[114:117], v84, s[10:11] offset:176
	global_load_dwordx4 v[118:121], v84, s[12:13] offset:160
	global_load_dwordx4 v[122:125], v84, s[12:13] offset:176
	s_waitcnt vmcnt(4)
	v_fmac_f32_e32 v148, v62, v94
	v_fmac_f32_e32 v149, v62, v95
	v_fmac_f32_e32 v150, v62, v96
	v_fmac_f32_e32 v151, v62, v97
	v_fmac_f32_e32 v152, v62, v98
	v_fmac_f32_e32 v153, v62, v99
	v_fmac_f32_e32 v154, v62, v100
	v_fmac_f32_e32 v155, v62, v101
	v_fmac_f32_e32 v156, v62, v102
	v_fmac_f32_e32 v157, v62, v103
	v_fmac_f32_e32 v158, v62, v104
	v_fmac_f32_e32 v159, v62, v105
	v_fmac_f32_e32 v160, v62, v106
	v_fmac_f32_e32 v161, v62, v107
	v_fmac_f32_e32 v162, v62, v108
	v_fmac_f32_e32 v163, v62, v109
	v_fmac_f32_e32 v170, v78, v94
	v_fmac_f32_e32 v171, v78, v95
	v_fmac_f32_e32 v172, v78, v96
	v_fmac_f32_e32 v173, v78, v97
	v_fmac_f32_e32 v174, v78, v98
	v_fmac_f32_e32 v175, v78, v99
	v_fmac_f32_e32 v176, v78, v100
	v_fmac_f32_e32 v177, v78, v101
	v_fmac_f32_e32 v178, v78, v102
	v_fmac_f32_e32 v179, v78, v103
	v_fmac_f32_e32 v180, v78, v104
	v_fmac_f32_e32 v181, v78, v105
	v_fmac_f32_e32 v182, v78, v106
	v_fmac_f32_e32 v183, v78, v107
	v_fmac_f32_e32 v184, v78, v108
	v_fmac_f32_e32 v185, v78, v109
	v_fmac_f32_e32 v186, v144, v94
	v_fmac_f32_e32 v187, v144, v95
	v_fmac_f32_e32 v188, v144, v96
	v_fmac_f32_e32 v189, v144, v97
	v_fmac_f32_e32 v190, v144, v98
	v_fmac_f32_e32 v191, v144, v99
	v_fmac_f32_e32 v192, v144, v100
	v_fmac_f32_e32 v193, v144, v101
	v_fmac_f32_e32 v194, v144, v102
	v_fmac_f32_e32 v195, v144, v103
	v_fmac_f32_e32 v196, v144, v104
	v_fmac_f32_e32 v197, v144, v105
	v_fmac_f32_e32 v198, v144, v106
	v_fmac_f32_e32 v199, v144, v107
	v_fmac_f32_e32 v200, v144, v108
	v_fmac_f32_e32 v201, v144, v109
	global_load_dwordx4 v[94:97], v84, s[10:11] offset:192
	global_load_dwordx4 v[98:101], v84, s[10:11] offset:208
	global_load_dwordx4 v[102:105], v84, s[12:13] offset:192
	global_load_dwordx4 v[106:109], v84, s[12:13] offset:208
	s_waitcnt vmcnt(4)
	v_fmac_f32_e32 v148, v63, v110
	v_fmac_f32_e32 v149, v63, v111
	v_fmac_f32_e32 v150, v63, v112
	v_fmac_f32_e32 v151, v63, v113
	v_fmac_f32_e32 v152, v63, v114
	v_fmac_f32_e32 v153, v63, v115
	v_fmac_f32_e32 v154, v63, v116
	v_fmac_f32_e32 v155, v63, v117
	v_fmac_f32_e32 v156, v63, v118
	v_fmac_f32_e32 v157, v63, v119
	v_fmac_f32_e32 v158, v63, v120
	v_fmac_f32_e32 v159, v63, v121
	v_fmac_f32_e32 v160, v63, v122
	v_fmac_f32_e32 v161, v63, v123
	v_fmac_f32_e32 v162, v63, v124
	v_fmac_f32_e32 v163, v63, v125
	v_fmac_f32_e32 v170, v79, v110
	v_fmac_f32_e32 v171, v79, v111
	v_fmac_f32_e32 v172, v79, v112
	v_fmac_f32_e32 v173, v79, v113
	v_fmac_f32_e32 v174, v79, v114
	v_fmac_f32_e32 v175, v79, v115
	v_fmac_f32_e32 v176, v79, v116
	v_fmac_f32_e32 v177, v79, v117
	v_fmac_f32_e32 v178, v79, v118
	v_fmac_f32_e32 v179, v79, v119
	v_fmac_f32_e32 v180, v79, v120
	v_fmac_f32_e32 v181, v79, v121
	v_fmac_f32_e32 v182, v79, v122
	v_fmac_f32_e32 v183, v79, v123
	v_fmac_f32_e32 v184, v79, v124
	v_fmac_f32_e32 v185, v79, v125
	v_fmac_f32_e32 v186, v145, v110
	v_fmac_f32_e32 v187, v145, v111
	v_fmac_f32_e32 v188, v145, v112
	v_fmac_f32_e32 v189, v145, v113
	v_fmac_f32_e32 v190, v145, v114
	v_fmac_f32_e32 v191, v145, v115
	v_fmac_f32_e32 v192, v145, v116
	v_fmac_f32_e32 v193, v145, v117
	v_fmac_f32_e32 v194, v145, v118
	v_fmac_f32_e32 v195, v145, v119
	v_fmac_f32_e32 v196, v145, v120
	v_fmac_f32_e32 v197, v145, v121
	v_fmac_f32_e32 v198, v145, v122
	v_fmac_f32_e32 v199, v145, v123
	v_fmac_f32_e32 v200, v145, v124
	v_fmac_f32_e32 v201, v145, v125
	global_load_dwordx4 v[110:113], v84, s[10:11] offset:224
	global_load_dwordx4 v[114:117], v84, s[10:11] offset:240
	global_load_dwordx4 v[118:121], v84, s[12:13] offset:224
	global_load_dwordx4 v[122:125], v84, s[12:13] offset:240
	s_waitcnt vmcnt(4)
	v_fmac_f32_e32 v148, v64, v94
	v_fmac_f32_e32 v149, v64, v95
	v_fmac_f32_e32 v150, v64, v96
	v_fmac_f32_e32 v151, v64, v97
	v_fmac_f32_e32 v152, v64, v98
	v_fmac_f32_e32 v153, v64, v99
	v_fmac_f32_e32 v154, v64, v100
	v_fmac_f32_e32 v155, v64, v101
	v_fmac_f32_e32 v156, v64, v102
	v_fmac_f32_e32 v157, v64, v103
	v_fmac_f32_e32 v158, v64, v104
	v_fmac_f32_e32 v159, v64, v105
	v_fmac_f32_e32 v160, v64, v106
	v_fmac_f32_e32 v161, v64, v107
	v_fmac_f32_e32 v162, v64, v108
	v_fmac_f32_e32 v163, v64, v109
	v_fmac_f32_e32 v170, v80, v94
	v_fmac_f32_e32 v171, v80, v95
	v_fmac_f32_e32 v172, v80, v96
	v_fmac_f32_e32 v173, v80, v97
	v_fmac_f32_e32 v174, v80, v98
	v_fmac_f32_e32 v175, v80, v99
	v_fmac_f32_e32 v176, v80, v100
	v_fmac_f32_e32 v177, v80, v101
	v_fmac_f32_e32 v178, v80, v102
	v_fmac_f32_e32 v179, v80, v103
	v_fmac_f32_e32 v180, v80, v104
	v_fmac_f32_e32 v181, v80, v105
	v_fmac_f32_e32 v182, v80, v106
	v_fmac_f32_e32 v183, v80, v107
	v_fmac_f32_e32 v184, v80, v108
	v_fmac_f32_e32 v185, v80, v109
	v_fmac_f32_e32 v186, v146, v94
	v_fmac_f32_e32 v187, v146, v95
	v_fmac_f32_e32 v188, v146, v96
	v_fmac_f32_e32 v189, v146, v97
	v_fmac_f32_e32 v190, v146, v98
	v_fmac_f32_e32 v191, v146, v99
	v_fmac_f32_e32 v192, v146, v100
	v_fmac_f32_e32 v193, v146, v101
	v_fmac_f32_e32 v194, v146, v102
	v_fmac_f32_e32 v195, v146, v103
	v_fmac_f32_e32 v196, v146, v104
	v_fmac_f32_e32 v197, v146, v105
	v_fmac_f32_e32 v198, v146, v106
	v_fmac_f32_e32 v199, v146, v107
	v_fmac_f32_e32 v200, v146, v108
	v_fmac_f32_e32 v201, v146, v109
	s_waitcnt vmcnt(0)
	v_fmac_f32_e32 v148, v65, v110
	v_fmac_f32_e32 v149, v65, v111
	v_fmac_f32_e32 v150, v65, v112
	v_fmac_f32_e32 v151, v65, v113
	v_fmac_f32_e32 v152, v65, v114
	v_fmac_f32_e32 v153, v65, v115
	v_fmac_f32_e32 v154, v65, v116
	v_fmac_f32_e32 v155, v65, v117
	v_fmac_f32_e32 v156, v65, v118
	v_fmac_f32_e32 v157, v65, v119
	v_fmac_f32_e32 v158, v65, v120
	v_fmac_f32_e32 v159, v65, v121
	v_fmac_f32_e32 v160, v65, v122
	v_fmac_f32_e32 v161, v65, v123
	v_fmac_f32_e32 v162, v65, v124
	v_fmac_f32_e32 v163, v65, v125
	v_fmac_f32_e32 v170, v81, v110
	v_fmac_f32_e32 v171, v81, v111
	v_fmac_f32_e32 v172, v81, v112
	v_fmac_f32_e32 v173, v81, v113
	v_fmac_f32_e32 v174, v81, v114
	v_fmac_f32_e32 v175, v81, v115
	v_fmac_f32_e32 v176, v81, v116
	v_fmac_f32_e32 v177, v81, v117
	v_fmac_f32_e32 v178, v81, v118
	v_fmac_f32_e32 v179, v81, v119
	v_fmac_f32_e32 v180, v81, v120
	v_fmac_f32_e32 v181, v81, v121
	v_fmac_f32_e32 v182, v81, v122
	v_fmac_f32_e32 v183, v81, v123
	v_fmac_f32_e32 v184, v81, v124
	v_fmac_f32_e32 v185, v81, v125
	v_fmac_f32_e32 v186, v147, v110
	v_fmac_f32_e32 v187, v147, v111
	v_fmac_f32_e32 v188, v147, v112
	v_fmac_f32_e32 v189, v147, v113
	v_fmac_f32_e32 v190, v147, v114
	v_fmac_f32_e32 v191, v147, v115
	v_fmac_f32_e32 v192, v147, v116
	v_fmac_f32_e32 v193, v147, v117
	v_fmac_f32_e32 v194, v147, v118
	v_fmac_f32_e32 v195, v147, v119
	v_fmac_f32_e32 v196, v147, v120
	v_fmac_f32_e32 v197, v147, v121
	v_fmac_f32_e32 v198, v147, v122
	v_fmac_f32_e32 v199, v147, v123
	v_fmac_f32_e32 v200, v147, v124
	v_fmac_f32_e32 v201, v147, v125
	s_nop 1
	v_permlane32_swap_b32_e32 v148, v156
	v_permlane32_swap_b32_e32 v149, v157
	v_permlane32_swap_b32_e32 v150, v158
	v_permlane32_swap_b32_e32 v151, v159
	v_permlane32_swap_b32_e32 v152, v160
	v_permlane32_swap_b32_e32 v153, v161
	v_permlane32_swap_b32_e32 v154, v162
	v_permlane32_swap_b32_e32 v155, v163
	v_permlane32_swap_b32_e32 v170, v178
	v_permlane32_swap_b32_e32 v171, v179
	v_permlane32_swap_b32_e32 v172, v180
	v_permlane32_swap_b32_e32 v173, v181
	v_permlane32_swap_b32_e32 v174, v182
	v_permlane32_swap_b32_e32 v175, v183
	v_permlane32_swap_b32_e32 v176, v184
	v_permlane32_swap_b32_e32 v177, v185
	v_permlane32_swap_b32_e32 v186, v194
	v_permlane32_swap_b32_e32 v187, v195
	v_permlane32_swap_b32_e32 v188, v196
	v_permlane32_swap_b32_e32 v189, v197
	v_permlane32_swap_b32_e32 v190, v198
	v_permlane32_swap_b32_e32 v191, v199
	v_permlane32_swap_b32_e32 v192, v200
	v_permlane32_swap_b32_e32 v193, v201
	v_add_f32_e32 v148, v148, v156
	v_add_f32_e32 v149, v149, v157
	v_add_f32_e32 v150, v150, v158
	v_add_f32_e32 v151, v151, v159
	v_add_f32_e32 v152, v152, v160
	v_add_f32_e32 v153, v153, v161
	v_add_f32_e32 v154, v154, v162
	v_add_f32_e32 v155, v155, v163
	v_add_f32_e32 v170, v170, v178
	v_add_f32_e32 v171, v171, v179
	v_add_f32_e32 v172, v172, v180
	v_add_f32_e32 v173, v173, v181
	v_add_f32_e32 v174, v174, v182
	v_add_f32_e32 v175, v175, v183
	v_add_f32_e32 v176, v176, v184
	v_add_f32_e32 v177, v177, v185
	v_add_f32_e32 v186, v186, v194
	v_add_f32_e32 v187, v187, v195
	v_add_f32_e32 v188, v188, v196
	v_add_f32_e32 v189, v189, v197
	v_add_f32_e32 v190, v190, v198
	v_add_f32_e32 v191, v191, v199
	v_add_f32_e32 v192, v192, v200
	v_add_f32_e32 v193, v193, v201
	s_nop 1
	v_permlane16_swap_b32_e32 v148, v152
	v_permlane16_swap_b32_e32 v149, v153
	v_permlane16_swap_b32_e32 v150, v154
	v_permlane16_swap_b32_e32 v151, v155
	v_permlane16_swap_b32_e32 v170, v174
	v_permlane16_swap_b32_e32 v171, v175
	v_permlane16_swap_b32_e32 v172, v176
	v_permlane16_swap_b32_e32 v173, v177
	v_permlane16_swap_b32_e32 v186, v190
	v_permlane16_swap_b32_e32 v187, v191
	v_permlane16_swap_b32_e32 v188, v192
	v_permlane16_swap_b32_e32 v189, v193
	v_add_f32_e32 v148, v148, v152
	v_add_f32_e32 v149, v149, v153
	v_add_f32_e32 v150, v150, v154
	v_add_f32_e32 v151, v151, v155
	v_add_f32_e32 v170, v170, v174
	v_add_f32_e32 v171, v171, v175
	v_add_f32_e32 v172, v172, v176
	v_add_f32_e32 v173, v173, v177
	v_add_f32_e32 v186, v186, v190
	v_add_f32_e32 v187, v187, v191
	v_add_f32_e32 v188, v188, v192
	v_add_f32_e32 v189, v189, v193
	s_nop 1
	v_add_f32_dpp v148, v148, v148 row_ror:8 row_mask:0xf bank_mask:0xf
	v_add_f32_dpp v149, v149, v149 row_ror:8 row_mask:0xf bank_mask:0xf
	v_add_f32_dpp v150, v150, v150 row_ror:8 row_mask:0xf bank_mask:0xf
	v_add_f32_dpp v151, v151, v151 row_ror:8 row_mask:0xf bank_mask:0xf
	v_add_f32_dpp v170, v170, v170 row_ror:8 row_mask:0xf bank_mask:0xf
	v_add_f32_dpp v171, v171, v171 row_ror:8 row_mask:0xf bank_mask:0xf
	v_add_f32_dpp v172, v172, v172 row_ror:8 row_mask:0xf bank_mask:0xf
	v_add_f32_dpp v173, v173, v173 row_ror:8 row_mask:0xf bank_mask:0xf
	v_add_f32_dpp v186, v186, v186 row_ror:8 row_mask:0xf bank_mask:0xf
	v_add_f32_dpp v187, v187, v187 row_ror:8 row_mask:0xf bank_mask:0xf
	v_add_f32_dpp v188, v188, v188 row_ror:8 row_mask:0xf bank_mask:0xf
	v_add_f32_dpp v189, v189, v189 row_ror:8 row_mask:0xf bank_mask:0xf
	v_add_f32_dpp v148, v148, v148 row_ror:4 row_mask:0xf bank_mask:0xf
	v_add_f32_dpp v149, v149, v149 row_ror:4 row_mask:0xf bank_mask:0xf
	v_add_f32_dpp v150, v150, v150 row_ror:4 row_mask:0xf bank_mask:0xf
	v_add_f32_dpp v151, v151, v151 row_ror:4 row_mask:0xf bank_mask:0xf
	v_add_f32_dpp v170, v170, v170 row_ror:4 row_mask:0xf bank_mask:0xf
	v_add_f32_dpp v171, v171, v171 row_ror:4 row_mask:0xf bank_mask:0xf
	v_add_f32_dpp v172, v172, v172 row_ror:4 row_mask:0xf bank_mask:0xf
	v_add_f32_dpp v173, v173, v173 row_ror:4 row_mask:0xf bank_mask:0xf
	v_add_f32_dpp v186, v186, v186 row_ror:4 row_mask:0xf bank_mask:0xf
	v_add_f32_dpp v187, v187, v187 row_ror:4 row_mask:0xf bank_mask:0xf
	v_add_f32_dpp v188, v188, v188 row_ror:4 row_mask:0xf bank_mask:0xf
	v_add_f32_dpp v189, v189, v189 row_ror:4 row_mask:0xf bank_mask:0xf
	v_add_f32_dpp v148, v148, v148 row_ror:2 row_mask:0xf bank_mask:0xf
	v_add_f32_dpp v149, v149, v149 row_ror:2 row_mask:0xf bank_mask:0xf
	v_add_f32_dpp v150, v150, v150 row_ror:2 row_mask:0xf bank_mask:0xf
	v_add_f32_dpp v151, v151, v151 row_ror:2 row_mask:0xf bank_mask:0xf
	v_add_f32_dpp v170, v170, v170 row_ror:2 row_mask:0xf bank_mask:0xf
	v_add_f32_dpp v171, v171, v171 row_ror:2 row_mask:0xf bank_mask:0xf
	v_add_f32_dpp v172, v172, v172 row_ror:2 row_mask:0xf bank_mask:0xf
	v_add_f32_dpp v173, v173, v173 row_ror:2 row_mask:0xf bank_mask:0xf
	v_add_f32_dpp v186, v186, v186 row_ror:2 row_mask:0xf bank_mask:0xf
	v_add_f32_dpp v187, v187, v187 row_ror:2 row_mask:0xf bank_mask:0xf
	v_add_f32_dpp v188, v188, v188 row_ror:2 row_mask:0xf bank_mask:0xf
	v_add_f32_dpp v189, v189, v189 row_ror:2 row_mask:0xf bank_mask:0xf
	v_add_f32_dpp v148, v148, v148 row_ror:1 row_mask:0xf bank_mask:0xf
	v_add_f32_dpp v149, v149, v149 row_ror:1 row_mask:0xf bank_mask:0xf
	v_add_f32_dpp v150, v150, v150 row_ror:1 row_mask:0xf bank_mask:0xf
	v_add_f32_dpp v151, v151, v151 row_ror:1 row_mask:0xf bank_mask:0xf
	v_add_f32_dpp v170, v170, v170 row_ror:1 row_mask:0xf bank_mask:0xf
	v_add_f32_dpp v171, v171, v171 row_ror:1 row_mask:0xf bank_mask:0xf
	v_add_f32_dpp v172, v172, v172 row_ror:1 row_mask:0xf bank_mask:0xf
	v_add_f32_dpp v173, v173, v173 row_ror:1 row_mask:0xf bank_mask:0xf
	v_add_f32_dpp v186, v186, v186 row_ror:1 row_mask:0xf bank_mask:0xf
	v_add_f32_dpp v187, v187, v187 row_ror:1 row_mask:0xf bank_mask:0xf
	v_add_f32_dpp v188, v188, v188 row_ror:1 row_mask:0xf bank_mask:0xf
	v_add_f32_dpp v189, v189, v189 row_ror:1 row_mask:0xf bank_mask:0xf
	v_cndmask_b32_e64 v218, v148, v149, s[16:17]
	v_cndmask_b32_e64 v218, v218, v150, s[18:19]
	v_cndmask_b32_e64 v218, v218, v151, s[22:23]
	v_add_f32_e32 v218, v218, v216
	v_cndmask_b32_e64 v219, v170, v171, s[16:17]
	v_cndmask_b32_e64 v219, v219, v172, s[18:19]
	v_cndmask_b32_e64 v219, v219, v173, s[22:23]
	v_add_f32_e32 v219, v219, v216
	v_cndmask_b32_e64 v220, v186, v187, s[16:17]
	v_cndmask_b32_e64 v220, v220, v188, s[18:19]
	v_cndmask_b32_e64 v220, v220, v189, s[22:23]
	v_add_f32_e32 v220, v220, v216
	v_mul_f32_e64 v221, |v218|, s14
	v_mul_f32_e64 v222, |v219|, s14
	v_mul_f32_e64 v223, |v220|, s14
	v_exp_f32_e32 v221, v221
	v_exp_f32_e32 v222, v222
	v_exp_f32_e32 v223, v223
	s_nop 0
	v_add_f32_e32 v221, 1.0, v221
	v_add_f32_e32 v222, 1.0, v222
	v_add_f32_e32 v223, 1.0, v223
	v_log_f32_e32 v221, v221
	v_log_f32_e32 v222, v222
	v_log_f32_e32 v223, v223
	s_nop 0
	v_mul_f32_e32 v221, s28, v221
	v_mul_f32_e32 v222, s28, v222
	v_mul_f32_e32 v223, s28, v223
	v_min_f32_e32 v126, 0, v218
	v_min_f32_e32 v127, 0, v219
	v_min_f32_e32 v128, 0, v220
	v_sub_f32_e32 v126, v126, v221
	v_sub_f32_e32 v127, v127, v222
	v_sub_f32_e32 v128, v128, v223
	v_cndmask_b32_e64 v218, v218, v126, s[48:49]
	v_cndmask_b32_e64 v219, v219, v127, s[48:49]
	v_cndmask_b32_e64 v220, v220, v128, s[48:49]
	s_mov_b64 s[24:25], exec
	s_mov_b64 exec, s[26:27]
	global_store_dword v217, v218, s[20:21] offset:0
	global_store_dword v217, v219, s[20:21] offset:64
	global_store_dword v217, v220, s[20:21] offset:128
	s_mov_b64 exec, s[24:25]
.Lnrm_pack:
	v_readlane_b32 s24, v255, 9
	v_readlane_b32 s25, v255, 10
	s_lshl_b64 s[22:23], s[80:81], 11
	s_add_u32 s24, s24, s22
	s_addc_u32 s25, s25, s23
	v_cvt_pk_bf16_f32 v2, v2, v3
	v_cvt_pk_bf16_f32 v3, v4, v5
	v_cvt_pk_bf16_f32 v4, v6, v7
	v_cvt_pk_bf16_f32 v5, v8, v9
	v_cvt_pk_bf16_f32 v10, v10, v11
	v_cvt_pk_bf16_f32 v11, v12, v13
	v_cvt_pk_bf16_f32 v12, v14, v15
	v_cvt_pk_bf16_f32 v13, v16, v17
	global_store_dwordx4 v83, v[2:5], s[24:25]
	global_store_dwordx4 v83, v[10:13], s[24:25] offset:1024
	s_add_u32 s24, s24, 0x800
	s_addc_u32 s25, s25, 0
	v_cvt_pk_bf16_f32 v18, v18, v19
	v_cvt_pk_bf16_f32 v19, v20, v21
	v_cvt_pk_bf16_f32 v20, v22, v23
	v_cvt_pk_bf16_f32 v21, v24, v25
	v_cvt_pk_bf16_f32 v26, v26, v27
	v_cvt_pk_bf16_f32 v27, v28, v29
	v_cvt_pk_bf16_f32 v28, v30, v31
	v_cvt_pk_bf16_f32 v29, v32, v33
	global_store_dwordx4 v83, v[18:21], s[24:25]
	global_store_dwordx4 v83, v[26:29], s[24:25] offset:1024
	s_add_u32 s24, s24, 0x800
	s_addc_u32 s25, s25, 0
	v_cvt_pk_bf16_f32 v34, v34, v35
	v_cvt_pk_bf16_f32 v35, v36, v37
	v_cvt_pk_bf16_f32 v36, v38, v39
	v_cvt_pk_bf16_f32 v37, v40, v41
	v_cvt_pk_bf16_f32 v42, v42, v43
	v_cvt_pk_bf16_f32 v43, v44, v45
	v_cvt_pk_bf16_f32 v44, v46, v47
	v_cvt_pk_bf16_f32 v45, v48, v49
	global_store_dwordx4 v83, v[34:37], s[24:25]
	global_store_dwordx4 v83, v[42:45], s[24:25] offset:1024
	s_add_u32 s24, s24, 0x800
	s_addc_u32 s25, s25, 0
	v_cvt_pk_bf16_f32 v50, v50, v51
	v_cvt_pk_bf16_f32 v51, v52, v53
	v_cvt_pk_bf16_f32 v52, v54, v55
	v_cvt_pk_bf16_f32 v53, v56, v57
	v_cvt_pk_bf16_f32 v58, v58, v59
	v_cvt_pk_bf16_f32 v59, v60, v61
	v_cvt_pk_bf16_f32 v60, v62, v63
	v_cvt_pk_bf16_f32 v61, v64, v65
	global_store_dwordx4 v83, v[50:53], s[24:25]
	global_store_dwordx4 v83, v[58:61], s[24:25] offset:1024
	s_add_u32 s24, s24, 0x800
	s_addc_u32 s25, s25, 0
	v_cvt_pk_bf16_f32 v66, v66, v67
	v_cvt_pk_bf16_f32 v67, v68, v69
	v_cvt_pk_bf16_f32 v68, v70, v71
	v_cvt_pk_bf16_f32 v69, v72, v73
	v_cvt_pk_bf16_f32 v74, v74, v75
	v_cvt_pk_bf16_f32 v75, v76, v77
	v_cvt_pk_bf16_f32 v76, v78, v79
	v_cvt_pk_bf16_f32 v77, v80, v81
	global_store_dwordx4 v83, v[66:69], s[24:25]
	global_store_dwordx4 v83, v[74:77], s[24:25] offset:1024
	s_add_u32 s24, s24, 0x800
	s_addc_u32 s25, s25, 0
	v_cvt_pk_bf16_f32 v132, v132, v133
	v_cvt_pk_bf16_f32 v133, v134, v135
	v_cvt_pk_bf16_f32 v134, v136, v137
	v_cvt_pk_bf16_f32 v135, v138, v139
	v_cvt_pk_bf16_f32 v140, v140, v141
	v_cvt_pk_bf16_f32 v141, v142, v143
	v_cvt_pk_bf16_f32 v142, v144, v145
	v_cvt_pk_bf16_f32 v143, v146, v147
	global_store_dwordx4 v83, v[132:135], s[24:25]
	global_store_dwordx4 v83, v[140:143], s[24:25] offset:1024
	s_branch .LBB0_1012
